# K-loops of P3-P6: the remaining eight VGPR-address LDS-DMA loads per iteration take the scalar base + VGPR offset form (4 SALU adds instead of 8 64-bit VALU adds)
# speedup vs baseline: 1.0037x; 1.0037x over previous
; #define PG8_STAGE(bufoff, gbase, voff) do { _Pragma("unroll") for (int _i = 0; _i < 2; ++_i) \
;         __builtin_amdgcn_global_load_lds((const unsigned*)((const char*)(gbase) + (voff)[_i]), (PG8_LAS unsigned*)(lds + (bufoff) + ldsw + _i * 8192), 16, 0, 0); } while (0)
; #define PG8_LDA(dst, b, h) do { _Pragma("unroll") for (int m = 0; m < 4; ++m) _Pragma("unroll") for (int k = 0; k < 2; ++k) dst[m][k] = *(const PG8_LAS bf16x8*)(lds + PG8_SA(b, h) + aoff + m * 2048 + k * 1024); } while (0)
; #define PG8_LDB(dst, b, h) do { _Pragma("unroll") for (int n = 0; n < 2; ++n) _Pragma("unroll") for (int k = 0; k < 2; ++k) dst[n][k] = *(const PG8_LAS bf16x8*)(lds + PG8_SB(b, h) + boff + n * 2048 + k * 1024); } while (0)
; #define PG8_MMA(ai, bj, At, Bt) do { __builtin_amdgcn_s_setprio(1); _Pragma("unroll") for (int m = 0; m < 4; ++m) _Pragma("unroll") for (int n = 0; n < 2; ++n) _Pragma("unroll") for (int k = 0; k < 2; ++k) \
;         acc[ai][bj][m][n] = __builtin_amdgcn_mfma_f32_16x16x32_bf16(Bt[n][k], At[m][k], acc[ai][bj][m][n], 0, 0, 0); __builtin_amdgcn_s_setprio(0); } while (0)
; #define PG8_WAIT_V(n) asm volatile("s_waitcnt vmcnt(" #n ")" ::: "memory")
; #define PG8_WAIT_L(n) asm volatile("s_waitcnt lgkmcnt(" #n ")" ::: "memory")
; #define PG8_BAR __builtin_amdgcn_s_barrier()
; #define PG8_SCHED __builtin_amdgcn_sched_barrier(0)
; template <class Epi, class Sched, bool ALIGN_EPI = false, bool SP2 = false>
; __device__ __forceinline__ void gemm_phase(PG8_LAS unsigned char* lds, const Gemm g, const Sched& S, const Epi& E) {
;     ...
;             PG8_LDB(B0, 0, 0); PG8_LDB(B1, 0, 1); PG8_SCHED; PG8_LDA(At, 0, 0); PG8_STAGE(PG8_SA(1, 1), a1 + hstep, voffA);
;             PG8_WAIT_V(8); PG8_WAIT_L(0); PG8_BAR; PG8_MMA(0, 0, At, B0); PG8_MMA(0, 1, At, B1); PG8_BAR; PG8_SCHED;
;             PG8_LDA(At, 0, 1); PG8_STAGE(PG8_SB(0, 0), b2, voffB); PG8_STAGE(PG8_SB(0, 1), b2 + hstep, voffB); PG8_STAGE(PG8_SA(0, 0), a2, voffA);
;             PG8_WAIT_V(8); PG8_WAIT_L(0); PG8_BAR; PG8_MMA(1, 0, At, B0); PG8_MMA(1, 1, At, B1); PG8_BAR; PG8_SCHED;
.LBB0_795:
	v_add_u32_e32 v162, s67, v186
	v_add_u32_e32 v178, s68, v186
	ds_read_b128 v[150:153], v162
	ds_read_b128 v[154:157], v162 offset:1024
	ds_read_b128 v[158:161], v162 offset:2048
	ds_read_b128 v[162:165], v162 offset:3072
	ds_read_b128 v[166:169], v178
	ds_read_b128 v[170:173], v178 offset:1024
	ds_read_b128 v[174:177], v178 offset:2048
	ds_read_b128 v[178:181], v178 offset:3072
	s_add_u32 s54, s46, 0xfff80080
	s_addc_u32 s55, s47, -1
	s_cmp_eq_u32 s82, 12
	s_cselect_b32 s57, s41, s55
	s_cselect_b32 s56, s78, s54
	s_cselect_b32 s55, s39, s81
	s_cselect_b32 s54, s79, s80
	s_add_i32 m0, s61, 0xc000
	ds_read_b128 v[182:185], v187
	ds_read_b128 v[190:193], v187 offset:1024
	ds_read_b128 v[194:197], v187 offset:2048
	ds_read_b128 v[198:201], v187 offset:3072
	ds_read_b128 v[202:205], v187 offset:4096
	ds_read_b128 v[206:209], v187 offset:5120
	ds_read_b128 v[210:213], v187 offset:6144
	ds_read_b128 v[214:217], v187 offset:7168
	global_load_lds_dwordx4 v142, s[46:47]
	s_add_i32 m0, s61, 0xe000
	s_nop 0
	global_load_lds_dwordx4 v144, s[46:47]
	s_waitcnt vmcnt(8)
	s_waitcnt lgkmcnt(0)
	s_barrier
	s_setprio 1
	v_mfma_f32_16x16x32_bf16 v[124:127], v[150:153], v[182:185], v[124:127]
	v_mfma_f32_16x16x32_bf16 v[120:123], v[158:161], v[182:185], v[120:123]
	v_mfma_f32_16x16x32_bf16 v[116:119], v[150:153], v[194:197], v[116:119]
	v_mfma_f32_16x16x32_bf16 v[112:115], v[158:161], v[194:197], v[112:115]
	v_mfma_f32_16x16x32_bf16 v[108:111], v[150:153], v[202:205], v[108:111]
	v_mfma_f32_16x16x32_bf16 v[104:107], v[158:161], v[202:205], v[104:107]
	v_mfma_f32_16x16x32_bf16 v[100:103], v[150:153], v[210:213], v[100:103]
	v_mfma_f32_16x16x32_bf16 v[96:99], v[158:161], v[210:213], v[96:99]
	v_mfma_f32_16x16x32_bf16 v[124:127], v[154:157], v[190:193], v[124:127]
	v_mfma_f32_16x16x32_bf16 v[120:123], v[162:165], v[190:193], v[120:123]
	v_mfma_f32_16x16x32_bf16 v[116:119], v[154:157], v[198:201], v[116:119]
	v_mfma_f32_16x16x32_bf16 v[112:115], v[162:165], v[198:201], v[112:115]
	v_mfma_f32_16x16x32_bf16 v[108:111], v[154:157], v[206:209], v[108:111]
	v_mfma_f32_16x16x32_bf16 v[104:107], v[162:165], v[206:209], v[104:107]
	v_mfma_f32_16x16x32_bf16 v[100:103], v[154:157], v[214:217], v[100:103]
	v_mfma_f32_16x16x32_bf16 v[96:99], v[162:165], v[214:217], v[96:99]
	v_mfma_f32_16x16x32_bf16 v[92:95], v[166:169], v[182:185], v[92:95]
	v_mfma_f32_16x16x32_bf16 v[88:91], v[174:177], v[182:185], v[88:91]
	v_mfma_f32_16x16x32_bf16 v[84:87], v[166:169], v[194:197], v[84:87]
	v_mfma_f32_16x16x32_bf16 v[80:83], v[174:177], v[194:197], v[80:83]
	v_mfma_f32_16x16x32_bf16 v[76:79], v[166:169], v[202:205], v[76:79]
	v_mfma_f32_16x16x32_bf16 v[72:75], v[174:177], v[202:205], v[72:75]
	v_mfma_f32_16x16x32_bf16 v[68:71], v[166:169], v[210:213], v[68:71]
	v_mfma_f32_16x16x32_bf16 v[64:67], v[174:177], v[210:213], v[64:67]
	v_mfma_f32_16x16x32_bf16 v[92:95], v[170:173], v[190:193], v[92:95]
	v_mfma_f32_16x16x32_bf16 v[88:91], v[178:181], v[190:193], v[88:91]
	v_mfma_f32_16x16x32_bf16 v[84:87], v[170:173], v[198:201], v[84:87]
	v_mfma_f32_16x16x32_bf16 v[80:83], v[178:181], v[198:201], v[80:83]
	v_mfma_f32_16x16x32_bf16 v[76:79], v[170:173], v[206:209], v[76:79]
	v_mfma_f32_16x16x32_bf16 v[72:75], v[178:181], v[206:209], v[72:75]
	v_mfma_f32_16x16x32_bf16 v[68:71], v[170:173], v[214:217], v[68:71]
	v_mfma_f32_16x16x32_bf16 v[64:67], v[178:181], v[214:217], v[64:67]
	s_setprio 0
	s_barrier
	s_add_u32 s92, s54, s14
	s_addc_u32 s93, s55, s15
	s_add_u32 s94, s56, s14
	s_addc_u32 s95, s57, s15
	s_add_i32 s83, s67, s60
	s_mov_b32 m0, s83
	ds_read_b128 v[182:185], v187 offset:16384
	ds_read_b128 v[190:193], v187 offset:17408
	ds_read_b128 v[194:197], v187 offset:18432
	ds_read_b128 v[198:201], v187 offset:19456
	ds_read_b128 v[202:205], v187 offset:20480
	ds_read_b128 v[206:209], v187 offset:21504
	ds_read_b128 v[210:213], v187 offset:22528
	ds_read_b128 v[214:217], v187 offset:23552
	global_load_lds_dwordx4 v130, s[54:55]
	s_add_i32 m0, s83, 0x2000
	s_add_u32 s86, s54, 0x80000
	s_addc_u32 s87, s55, 0
	s_add_i32 s83, s68, s60
	global_load_lds_dwordx4 v134, s[54:55]
	s_mov_b32 m0, s83
	s_nop 0
	global_load_lds_dwordx4 v130, s[86:87]
	s_add_i32 m0, s83, 0x2000
	s_nop 0
	global_load_lds_dwordx4 v134, s[86:87]
	s_mov_b32 m0, s61
	s_nop 0
	global_load_lds_dwordx4 v128, s[56:57]
	s_mov_b32 m0, s62
	s_nop 0
	global_load_lds_dwordx4 v132, s[56:57]
	s_waitcnt vmcnt(8)
	s_waitcnt lgkmcnt(0)
	s_barrier
	s_setprio 1
	v_mfma_f32_16x16x32_bf16 v[60:63], v[150:153], v[182:185], v[60:63]
	v_mfma_f32_16x16x32_bf16 v[56:59], v[158:161], v[182:185], v[56:59]
	v_mfma_f32_16x16x32_bf16 v[52:55], v[150:153], v[194:197], v[52:55]
	v_mfma_f32_16x16x32_bf16 v[48:51], v[158:161], v[194:197], v[48:51]
	v_mfma_f32_16x16x32_bf16 v[44:47], v[150:153], v[202:205], v[44:47]
	v_mfma_f32_16x16x32_bf16 v[40:43], v[158:161], v[202:205], v[40:43]
	v_mfma_f32_16x16x32_bf16 v[36:39], v[150:153], v[210:213], v[36:39]
	v_mfma_f32_16x16x32_bf16 v[32:35], v[158:161], v[210:213], v[32:35]
	v_mfma_f32_16x16x32_bf16 v[60:63], v[154:157], v[190:193], v[60:63]
	v_mfma_f32_16x16x32_bf16 v[56:59], v[162:165], v[190:193], v[56:59]
	v_mfma_f32_16x16x32_bf16 v[52:55], v[154:157], v[198:201], v[52:55]
	v_mfma_f32_16x16x32_bf16 v[48:51], v[162:165], v[198:201], v[48:51]
	v_mfma_f32_16x16x32_bf16 v[44:47], v[154:157], v[206:209], v[44:47]
	v_mfma_f32_16x16x32_bf16 v[40:43], v[162:165], v[206:209], v[40:43]
	v_mfma_f32_16x16x32_bf16 v[36:39], v[154:157], v[214:217], v[36:39]
	v_mfma_f32_16x16x32_bf16 v[32:35], v[162:165], v[214:217], v[32:35]
	v_mfma_f32_16x16x32_bf16 v[28:31], v[166:169], v[182:185], v[28:31]
	v_mfma_f32_16x16x32_bf16 v[24:27], v[174:177], v[182:185], v[24:27]
	v_mfma_f32_16x16x32_bf16 v[20:23], v[166:169], v[194:197], v[20:23]
	v_mfma_f32_16x16x32_bf16 v[16:19], v[174:177], v[194:197], v[16:19]
	v_mfma_f32_16x16x32_bf16 v[12:15], v[166:169], v[202:205], v[12:15]
	v_mfma_f32_16x16x32_bf16 v[8:11], v[174:177], v[202:205], v[8:11]
	v_mfma_f32_16x16x32_bf16 v[4:7], v[166:169], v[210:213], v[4:7]
	v_mfma_f32_16x16x32_bf16 v[0:3], v[174:177], v[210:213], v[0:3]
	v_mfma_f32_16x16x32_bf16 v[28:31], v[170:173], v[190:193], v[28:31]
	v_mfma_f32_16x16x32_bf16 v[24:27], v[178:181], v[190:193], v[24:27]
	v_mfma_f32_16x16x32_bf16 v[20:23], v[170:173], v[198:201], v[20:23]
	v_mfma_f32_16x16x32_bf16 v[16:19], v[178:181], v[198:201], v[16:19]
	v_mfma_f32_16x16x32_bf16 v[12:15], v[170:173], v[206:209], v[12:15]
	v_mfma_f32_16x16x32_bf16 v[8:11], v[178:181], v[206:209], v[8:11]
	v_mfma_f32_16x16x32_bf16 v[4:7], v[170:173], v[214:217], v[4:7]
	v_mfma_f32_16x16x32_bf16 v[0:3], v[178:181], v[214:217], v[0:3]
	s_setprio 0
	s_barrier
; #define PG8_STAGE(bufoff, gbase, voff) do { _Pragma("unroll") for (int _i = 0; _i < 2; ++_i) \
;         __builtin_amdgcn_global_load_lds((const unsigned*)((const char*)(gbase) + (voff)[_i]), (PG8_LAS unsigned*)(lds + (bufoff) + ldsw + _i * 8192), 16, 0, 0); } while (0)
; #define PG8_LDA(dst, b, h) do { _Pragma("unroll") for (int m = 0; m < 4; ++m) _Pragma("unroll") for (int k = 0; k < 2; ++k) dst[m][k] = *(const PG8_LAS bf16x8*)(lds + PG8_SA(b, h) + aoff + m * 2048 + k * 1024); } while (0)
; #define PG8_LDB(dst, b, h) do { _Pragma("unroll") for (int n = 0; n < 2; ++n) _Pragma("unroll") for (int k = 0; k < 2; ++k) dst[n][k] = *(const PG8_LAS bf16x8*)(lds + PG8_SB(b, h) + boff + n * 2048 + k * 1024); } while (0)
; #define PG8_MMA(ai, bj, At, Bt) do { __builtin_amdgcn_s_setprio(1); _Pragma("unroll") for (int m = 0; m < 4; ++m) _Pragma("unroll") for (int n = 0; n < 2; ++n) _Pragma("unroll") for (int k = 0; k < 2; ++k) \
;         acc[ai][bj][m][n] = __builtin_amdgcn_mfma_f32_16x16x32_bf16(Bt[n][k], At[m][k], acc[ai][bj][m][n], 0, 0, 0); __builtin_amdgcn_s_setprio(0); } while (0)
; #define PG8_WAIT_V(n) asm volatile("s_waitcnt vmcnt(" #n ")" ::: "memory")
; #define PG8_WAIT_L(n) asm volatile("s_waitcnt lgkmcnt(" #n ")" ::: "memory")
; #define PG8_BAR __builtin_amdgcn_s_barrier()
; #define PG8_SCHED __builtin_amdgcn_sched_barrier(0)
; template <class Epi, class Sched, bool ALIGN_EPI = false, bool SP2 = false>
; __device__ __forceinline__ void gemm_phase(PG8_LAS unsigned char* lds, const Gemm g, const Sched& S, const Epi& E) {
;     ...
;             PG8_LDB(B0, 1, 0); PG8_LDB(B1, 1, 1); PG8_SCHED; PG8_LDA(At, 1, 0); PG8_STAGE(PG8_SA(0, 1), a2 + hstep, voffA);
;             PG8_WAIT_V(8); PG8_WAIT_L(0); PG8_BAR; PG8_MMA(0, 0, At, B0); PG8_MMA(0, 1, At, B1); PG8_BAR; PG8_SCHED;
;             PG8_LDA(At, 1, 1); PG8_STAGE(PG8_SB(1, 0), b3, voffB); PG8_STAGE(PG8_SB(1, 1), b3 + hstep, voffB); PG8_STAGE(PG8_SA(1, 0), a3, voffA);
;             PG8_WAIT_V(8); PG8_WAIT_L(0); PG8_BAR; PG8_MMA(1, 0, At, B0); PG8_MMA(1, 1, At, B1); PG8_BAR; PG8_SCHED;
	s_add_i32 s83, 0, 0x18000
	s_add_i32 s86, 0, 0x1c000
	v_add_u32_e32 v162, s83, v186
	v_add_u32_e32 v178, s86, v186
	ds_read_b128 v[150:153], v162
	ds_read_b128 v[154:157], v162 offset:1024
	ds_read_b128 v[158:161], v162 offset:2048
	ds_read_b128 v[162:165], v162 offset:3072
	ds_read_b128 v[166:169], v178
	ds_read_b128 v[170:173], v178 offset:1024
	ds_read_b128 v[174:177], v178 offset:2048
	ds_read_b128 v[178:181], v178 offset:3072
	s_add_u32 s56, s56, 0x80000
	s_addc_u32 s57, s57, 0
	s_mov_b32 m0, s63
	ds_read_b128 v[182:185], v187 offset:32768
	ds_read_b128 v[190:193], v187 offset:33792
	ds_read_b128 v[194:197], v187 offset:34816
	ds_read_b128 v[198:201], v187 offset:35840
	ds_read_b128 v[202:205], v187 offset:36864
	ds_read_b128 v[206:209], v187 offset:37888
	ds_read_b128 v[210:213], v187 offset:38912
	ds_read_b128 v[214:217], v187 offset:39936
	global_load_lds_dwordx4 v128, s[56:57]
	s_mov_b32 m0, s64
	s_nop 0
	global_load_lds_dwordx4 v132, s[56:57]
	s_waitcnt vmcnt(8)
	s_waitcnt lgkmcnt(0)
	s_barrier
	s_setprio 1
	v_mfma_f32_16x16x32_bf16 v[124:127], v[150:153], v[182:185], v[124:127]
	v_mfma_f32_16x16x32_bf16 v[120:123], v[158:161], v[182:185], v[120:123]
	v_mfma_f32_16x16x32_bf16 v[116:119], v[150:153], v[194:197], v[116:119]
	v_mfma_f32_16x16x32_bf16 v[112:115], v[158:161], v[194:197], v[112:115]
	v_mfma_f32_16x16x32_bf16 v[108:111], v[150:153], v[202:205], v[108:111]
	v_mfma_f32_16x16x32_bf16 v[104:107], v[158:161], v[202:205], v[104:107]
	v_mfma_f32_16x16x32_bf16 v[100:103], v[150:153], v[210:213], v[100:103]
	v_mfma_f32_16x16x32_bf16 v[96:99], v[158:161], v[210:213], v[96:99]
	v_mfma_f32_16x16x32_bf16 v[124:127], v[154:157], v[190:193], v[124:127]
	v_mfma_f32_16x16x32_bf16 v[120:123], v[162:165], v[190:193], v[120:123]
	v_mfma_f32_16x16x32_bf16 v[116:119], v[154:157], v[198:201], v[116:119]
	v_mfma_f32_16x16x32_bf16 v[112:115], v[162:165], v[198:201], v[112:115]
	v_mfma_f32_16x16x32_bf16 v[108:111], v[154:157], v[206:209], v[108:111]
	v_mfma_f32_16x16x32_bf16 v[104:107], v[162:165], v[206:209], v[104:107]
	v_mfma_f32_16x16x32_bf16 v[100:103], v[154:157], v[214:217], v[100:103]
	v_mfma_f32_16x16x32_bf16 v[96:99], v[162:165], v[214:217], v[96:99]
	v_mfma_f32_16x16x32_bf16 v[92:95], v[166:169], v[182:185], v[92:95]
	v_mfma_f32_16x16x32_bf16 v[88:91], v[174:177], v[182:185], v[88:91]
	v_mfma_f32_16x16x32_bf16 v[84:87], v[166:169], v[194:197], v[84:87]
	v_mfma_f32_16x16x32_bf16 v[80:83], v[174:177], v[194:197], v[80:83]
	v_mfma_f32_16x16x32_bf16 v[76:79], v[166:169], v[202:205], v[76:79]
	v_mfma_f32_16x16x32_bf16 v[72:75], v[174:177], v[202:205], v[72:75]
	v_mfma_f32_16x16x32_bf16 v[68:71], v[166:169], v[210:213], v[68:71]
	v_mfma_f32_16x16x32_bf16 v[64:67], v[174:177], v[210:213], v[64:67]
	v_mfma_f32_16x16x32_bf16 v[92:95], v[170:173], v[190:193], v[92:95]
	v_mfma_f32_16x16x32_bf16 v[88:91], v[178:181], v[190:193], v[88:91]
	v_mfma_f32_16x16x32_bf16 v[84:87], v[170:173], v[198:201], v[84:87]
	v_mfma_f32_16x16x32_bf16 v[80:83], v[178:181], v[198:201], v[80:83]
	v_mfma_f32_16x16x32_bf16 v[76:79], v[170:173], v[206:209], v[76:79]
	v_mfma_f32_16x16x32_bf16 v[72:75], v[178:181], v[206:209], v[72:75]
	v_mfma_f32_16x16x32_bf16 v[68:71], v[170:173], v[214:217], v[68:71]
	v_mfma_f32_16x16x32_bf16 v[64:67], v[178:181], v[214:217], v[64:67]
	s_setprio 0
	s_barrier
	s_add_i32 s56, s83, s60
	s_mov_b32 m0, s56
	ds_read_b128 v[182:185], v187 offset:49152
	ds_read_b128 v[190:193], v187 offset:50176
	ds_read_b128 v[194:197], v187 offset:51200
	ds_read_b128 v[198:201], v187 offset:52224
	ds_read_b128 v[202:205], v187 offset:53248
	ds_read_b128 v[206:209], v187 offset:54272
	ds_read_b128 v[210:213], v187 offset:55296
	ds_read_b128 v[214:217], v187 offset:56320
	global_load_lds_dwordx4 v130, s[92:93]
	s_add_i32 m0, s56, 0x2000
	s_add_u32 s54, s54, 0x80080
	s_addc_u32 s55, s55, 0
	s_add_i32 s56, s86, s60
	global_load_lds_dwordx4 v134, s[92:93]
	s_mov_b32 m0, s56
	s_nop 0
	global_load_lds_dwordx4 v130, s[54:55]
	s_add_i32 m0, s56, 0x2000
	s_nop 0
	global_load_lds_dwordx4 v134, s[54:55]
	s_mov_b32 m0, s65
	s_nop 0
	global_load_lds_dwordx4 v128, s[94:95]
	s_mov_b32 m0, s66
	s_nop 0
	global_load_lds_dwordx4 v132, s[94:95]
	s_waitcnt vmcnt(8)
	s_waitcnt lgkmcnt(0)
	s_barrier
	s_setprio 1
	v_mfma_f32_16x16x32_bf16 v[60:63], v[150:153], v[182:185], v[60:63]
	v_mfma_f32_16x16x32_bf16 v[56:59], v[158:161], v[182:185], v[56:59]
	v_mfma_f32_16x16x32_bf16 v[52:55], v[150:153], v[194:197], v[52:55]
	v_mfma_f32_16x16x32_bf16 v[48:51], v[158:161], v[194:197], v[48:51]
	v_mfma_f32_16x16x32_bf16 v[44:47], v[150:153], v[202:205], v[44:47]
	v_mfma_f32_16x16x32_bf16 v[40:43], v[158:161], v[202:205], v[40:43]
	v_mfma_f32_16x16x32_bf16 v[36:39], v[150:153], v[210:213], v[36:39]
	v_mfma_f32_16x16x32_bf16 v[32:35], v[158:161], v[210:213], v[32:35]
	v_mfma_f32_16x16x32_bf16 v[60:63], v[154:157], v[190:193], v[60:63]
	v_mfma_f32_16x16x32_bf16 v[56:59], v[162:165], v[190:193], v[56:59]
	v_mfma_f32_16x16x32_bf16 v[52:55], v[154:157], v[198:201], v[52:55]
	v_mfma_f32_16x16x32_bf16 v[48:51], v[162:165], v[198:201], v[48:51]
	v_mfma_f32_16x16x32_bf16 v[44:47], v[154:157], v[206:209], v[44:47]
	v_mfma_f32_16x16x32_bf16 v[40:43], v[162:165], v[206:209], v[40:43]
	v_mfma_f32_16x16x32_bf16 v[36:39], v[154:157], v[214:217], v[36:39]
	v_mfma_f32_16x16x32_bf16 v[32:35], v[162:165], v[214:217], v[32:35]
	v_mfma_f32_16x16x32_bf16 v[28:31], v[166:169], v[182:185], v[28:31]
	v_mfma_f32_16x16x32_bf16 v[24:27], v[174:177], v[182:185], v[24:27]
	v_mfma_f32_16x16x32_bf16 v[20:23], v[166:169], v[194:197], v[20:23]
	v_mfma_f32_16x16x32_bf16 v[16:19], v[174:177], v[194:197], v[16:19]
	v_mfma_f32_16x16x32_bf16 v[12:15], v[166:169], v[202:205], v[12:15]
	v_mfma_f32_16x16x32_bf16 v[8:11], v[174:177], v[202:205], v[8:11]
	v_mfma_f32_16x16x32_bf16 v[4:7], v[166:169], v[210:213], v[4:7]
	v_mfma_f32_16x16x32_bf16 v[0:3], v[174:177], v[210:213], v[0:3]
	v_mfma_f32_16x16x32_bf16 v[28:31], v[170:173], v[190:193], v[28:31]
	v_mfma_f32_16x16x32_bf16 v[24:27], v[178:181], v[190:193], v[24:27]
	v_mfma_f32_16x16x32_bf16 v[20:23], v[170:173], v[198:201], v[20:23]
	v_mfma_f32_16x16x32_bf16 v[16:19], v[178:181], v[198:201], v[16:19]
	v_mfma_f32_16x16x32_bf16 v[12:15], v[170:173], v[206:209], v[12:15]
	v_mfma_f32_16x16x32_bf16 v[8:11], v[178:181], v[206:209], v[8:11]
	v_mfma_f32_16x16x32_bf16 v[4:7], v[170:173], v[214:217], v[4:7]
	v_mfma_f32_16x16x32_bf16 v[0:3], v[178:181], v[214:217], v[0:3]
	s_setprio 0
	s_barrier
	s_add_i32 s82, s82, 2
	s_add_u32 s46, s46, 0x100
	s_addc_u32 s47, s47, 0
	s_add_u32 s80, s80, 0x100
	s_addc_u32 s81, s81, 0
	s_cmp_gt_u32 s82, 13
	s_cbranch_scc0 .LBB0_795
	s_and_b64 vcc, exec, s[16:17]
	s_cbranch_vccz .LBB0_798
	s_barrier

; #define PG8_STAGE(bufoff, gbase, voff) do { _Pragma("unroll") for (int _i = 0; _i < 2; ++_i) \
;         __builtin_amdgcn_global_load_lds((const unsigned*)((const char*)(gbase) + (voff)[_i]), (PG8_LAS unsigned*)(lds + (bufoff) + ldsw + _i * 8192), 16, 0, 0); } while (0)
; #define PG8_LDA(dst, b, h) do { _Pragma("unroll") for (int m = 0; m < 4; ++m) _Pragma("unroll") for (int k = 0; k < 2; ++k) dst[m][k] = *(const PG8_LAS bf16x8*)(lds + PG8_SA(b, h) + aoff + m * 2048 + k * 1024); } while (0)
; #define PG8_LDB(dst, b, h) do { _Pragma("unroll") for (int n = 0; n < 2; ++n) _Pragma("unroll") for (int k = 0; k < 2; ++k) dst[n][k] = *(const PG8_LAS bf16x8*)(lds + PG8_SB(b, h) + boff + n * 2048 + k * 1024); } while (0)
; #define PG8_MMA(ai, bj, At, Bt) do { __builtin_amdgcn_s_setprio(1); _Pragma("unroll") for (int m = 0; m < 4; ++m) _Pragma("unroll") for (int n = 0; n < 2; ++n) _Pragma("unroll") for (int k = 0; k < 2; ++k) \
;         acc[ai][bj][m][n] = __builtin_amdgcn_mfma_f32_16x16x32_bf16(Bt[n][k], At[m][k], acc[ai][bj][m][n], 0, 0, 0); __builtin_amdgcn_s_setprio(0); } while (0)
; #define PG8_WAIT_V(n) asm volatile("s_waitcnt vmcnt(" #n ")" ::: "memory")
; #define PG8_WAIT_L(n) asm volatile("s_waitcnt lgkmcnt(" #n ")" ::: "memory")
; template <class Epi, class Sched, bool ALIGN_EPI = false, bool SP2 = false>
; __device__ __forceinline__ void gemm_phase(PG8_LAS unsigned char* lds, const Gemm g, const Sched& S, const Epi& E) {
;     ...
;             const bool last = (t == nt - 2);
;             const char* a1 = cA + (size_t)(t + 1) * kstep;
;             const char* a2 = last ? nA : cA + (size_t)(t + 2) * kstep; const char* b2 = last ? nB : cB + (size_t)(t + 2) * kstep;
;             const char* a3 = a2 + kstep; const char* b3 = b2 + kstep;
;             if (last && has_next) S.a_ready(nxt);
;             if constexpr (SP2) {
;             PG8_LDB(B0, 0, 0); PG8_LDB(B1, 0, 1); PG8_SCHED; PG8_LDA(At, 0, 0); PG8_STAGE(PG8_SA(1, 1), a1 + hstep, voffA);
;             PG8_WAIT_V(8); PG8_WAIT_L(0); PG8_BAR; PG8_MMA(0, 0, At, B0); PG8_MMA(0, 1, At, B1); PG8_BAR; PG8_SCHED;
;             PG8_LDA(At, 0, 1); PG8_STAGE(PG8_SB(0, 0), b2, voffB); PG8_STAGE(PG8_SB(0, 1), b2 + hstep, voffB); PG8_STAGE(PG8_SA(0, 0), a2, voffA);
;             PG8_WAIT_V(8); PG8_WAIT_L(0); PG8_BAR; PG8_MMA(1, 0, At, B0); PG8_MMA(1, 1, At, B1); PG8_BAR; PG8_SCHED;
.LBB0_881:
	s_ashr_i32 s23, s22, 31
	s_lshl_b64 s[24:25], s[22:23], 19
	s_add_u32 s24, s38, s24
	s_addc_u32 s25, s39, s25
	s_and_b64 s[26:27], s[4:5], exec
	s_cselect_b32 s23, s25, s31
	s_cselect_b32 s29, s24, s30
	s_ashr_i32 s21, s20, 31
	s_lshl_b64 s[26:27], s[20:21], 19
	s_add_u32 s26, s40, s26
	s_addc_u32 s27, s41, s27
	s_and_b64 s[36:37], s[4:5], exec
	s_cselect_b32 s21, s27, s35
	s_cselect_b32 s58, s26, s34
	s_add_u32 s30, s30, 0x40080
	s_addc_u32 s31, s31, 0
	s_add_u32 s59, s34, 0x100
	s_addc_u32 s60, s35, 0
	s_mov_b32 s61, -2
	s_waitcnt lgkmcnt(0)
	ds_read_b128 v[128:131], v173
	ds_read_b128 v[132:135], v173 offset:1024
	ds_read_b128 v[136:139], v173 offset:2048
	ds_read_b128 v[140:143], v173 offset:3072
	ds_read_b128 v[164:167], v174
	ds_read_b128 v[168:171], v174 offset:1024
	ds_read_b128 v[178:181], v174 offset:2048
	ds_read_b128 v[182:185], v174 offset:3072
	s_add_u32 s34, s30, 0xfffc0080
	s_addc_u32 s35, s31, -1
	s_cmp_eq_u32 s61, 12
	s_cselect_b32 s37, s23, s35
	s_cselect_b32 s36, s29, s34
	s_cselect_b32 s35, s21, s60
	s_cselect_b32 s34, s58, s59
	s_add_i32 m0, s43, 0xc000
	ds_read_b128 v[190:193], v175
	ds_read_b128 v[194:197], v175 offset:1024
	ds_read_b128 v[198:201], v175 offset:2048
	ds_read_b128 v[202:205], v175 offset:3072
	ds_read_b128 v[206:209], v175 offset:4096
	ds_read_b128 v[210:213], v175 offset:5120
	ds_read_b128 v[214:217], v175 offset:6144
	ds_read_b128 v[218:221], v175 offset:7168
	global_load_lds_dwordx4 v156, s[30:31]
	s_add_i32 m0, s43, 0xe000
	s_nop 0
	global_load_lds_dwordx4 v158, s[30:31]
	s_waitcnt vmcnt(8)
	s_waitcnt lgkmcnt(0)
	s_barrier
	s_setprio 1
	v_mfma_f32_16x16x32_bf16 v[124:127], v[128:131], v[190:193], 0
	v_mfma_f32_16x16x32_bf16 v[120:123], v[136:139], v[190:193], 0
	v_mfma_f32_16x16x32_bf16 v[108:111], v[128:131], v[198:201], 0
	v_mfma_f32_16x16x32_bf16 v[104:107], v[136:139], v[198:201], 0
	v_mfma_f32_16x16x32_bf16 v[92:95], v[128:131], v[206:209], 0
	v_mfma_f32_16x16x32_bf16 v[88:91], v[136:139], v[206:209], 0
	v_mfma_f32_16x16x32_bf16 v[76:79], v[128:131], v[214:217], 0
	v_mfma_f32_16x16x32_bf16 v[72:75], v[136:139], v[214:217], 0
	v_mfma_f32_16x16x32_bf16 v[124:127], v[132:135], v[194:197], v[124:127]
	v_mfma_f32_16x16x32_bf16 v[120:123], v[140:143], v[194:197], v[120:123]
	v_mfma_f32_16x16x32_bf16 v[108:111], v[132:135], v[202:205], v[108:111]
	v_mfma_f32_16x16x32_bf16 v[104:107], v[140:143], v[202:205], v[104:107]
	v_mfma_f32_16x16x32_bf16 v[92:95], v[132:135], v[210:213], v[92:95]
	v_mfma_f32_16x16x32_bf16 v[88:91], v[140:143], v[210:213], v[88:91]
	v_mfma_f32_16x16x32_bf16 v[76:79], v[132:135], v[218:221], v[76:79]
	v_mfma_f32_16x16x32_bf16 v[72:75], v[140:143], v[218:221], v[72:75]
	v_mfma_f32_16x16x32_bf16 v[116:119], v[164:167], v[190:193], 0
	v_mfma_f32_16x16x32_bf16 v[112:115], v[178:181], v[190:193], 0
	v_mfma_f32_16x16x32_bf16 v[100:103], v[164:167], v[198:201], 0
	v_mfma_f32_16x16x32_bf16 v[96:99], v[178:181], v[198:201], 0
	v_mfma_f32_16x16x32_bf16 v[84:87], v[164:167], v[206:209], 0
	v_mfma_f32_16x16x32_bf16 v[80:83], v[178:181], v[206:209], 0
	v_mfma_f32_16x16x32_bf16 v[68:71], v[164:167], v[214:217], 0
	v_mfma_f32_16x16x32_bf16 v[64:67], v[178:181], v[214:217], 0
	v_mfma_f32_16x16x32_bf16 v[116:119], v[168:171], v[194:197], v[116:119]
	v_mfma_f32_16x16x32_bf16 v[112:115], v[182:185], v[194:197], v[112:115]
	v_mfma_f32_16x16x32_bf16 v[100:103], v[168:171], v[202:205], v[100:103]
	v_mfma_f32_16x16x32_bf16 v[96:99], v[182:185], v[202:205], v[96:99]
	v_mfma_f32_16x16x32_bf16 v[84:87], v[168:171], v[210:213], v[84:87]
	v_mfma_f32_16x16x32_bf16 v[80:83], v[182:185], v[210:213], v[80:83]
	v_mfma_f32_16x16x32_bf16 v[68:71], v[168:171], v[218:221], v[68:71]
	v_mfma_f32_16x16x32_bf16 v[64:67], v[182:185], v[218:221], v[64:67]
	s_setprio 0
	s_barrier
	s_add_u32 s92, s34, s16
	s_addc_u32 s93, s35, s17
	s_add_u32 s94, s36, s16
	s_addc_u32 s95, s37, s17
	s_add_i32 s62, s55, s42
	s_mov_b32 m0, s62
	ds_read_b128 v[190:193], v175 offset:16384
	ds_read_b128 v[194:197], v175 offset:17408
	ds_read_b128 v[198:201], v175 offset:18432
	ds_read_b128 v[202:205], v175 offset:19456
	ds_read_b128 v[206:209], v175 offset:20480
	ds_read_b128 v[210:213], v175 offset:21504
	ds_read_b128 v[214:217], v175 offset:22528
	ds_read_b128 v[218:221], v175 offset:23552
	global_load_lds_dwordx4 v146, s[34:35]
	s_add_i32 m0, s62, 0x2000
	s_add_u32 s62, s34, 0x40000
	s_addc_u32 s63, s35, 0
	s_add_i32 s64, s56, s42
	global_load_lds_dwordx4 v150, s[34:35]
	s_mov_b32 m0, s64
	s_nop 0
	global_load_lds_dwordx4 v146, s[62:63]
	s_add_i32 m0, s64, 0x2000
	s_nop 0
	global_load_lds_dwordx4 v150, s[62:63]
	s_mov_b32 m0, s43
	s_nop 0
	global_load_lds_dwordx4 v144, s[36:37]
	s_mov_b32 m0, s44
	s_nop 0
	global_load_lds_dwordx4 v148, s[36:37]
	s_waitcnt vmcnt(8)
	s_waitcnt lgkmcnt(0)
	s_barrier
	s_setprio 1
	v_mfma_f32_16x16x32_bf16 v[60:63], v[128:131], v[190:193], 0
	v_mfma_f32_16x16x32_bf16 v[56:59], v[136:139], v[190:193], 0
	v_mfma_f32_16x16x32_bf16 v[44:47], v[128:131], v[198:201], 0
	v_mfma_f32_16x16x32_bf16 v[40:43], v[136:139], v[198:201], 0
	v_mfma_f32_16x16x32_bf16 v[28:31], v[128:131], v[206:209], 0
	v_mfma_f32_16x16x32_bf16 v[24:27], v[136:139], v[206:209], 0
	v_mfma_f32_16x16x32_bf16 v[12:15], v[128:131], v[214:217], 0
	v_mfma_f32_16x16x32_bf16 v[8:11], v[136:139], v[214:217], 0
	v_mfma_f32_16x16x32_bf16 v[60:63], v[132:135], v[194:197], v[60:63]
	v_mfma_f32_16x16x32_bf16 v[56:59], v[140:143], v[194:197], v[56:59]
	v_mfma_f32_16x16x32_bf16 v[44:47], v[132:135], v[202:205], v[44:47]
	v_mfma_f32_16x16x32_bf16 v[40:43], v[140:143], v[202:205], v[40:43]
	v_mfma_f32_16x16x32_bf16 v[28:31], v[132:135], v[210:213], v[28:31]
	v_mfma_f32_16x16x32_bf16 v[24:27], v[140:143], v[210:213], v[24:27]
	v_mfma_f32_16x16x32_bf16 v[12:15], v[132:135], v[218:221], v[12:15]
	v_mfma_f32_16x16x32_bf16 v[8:11], v[140:143], v[218:221], v[8:11]
	v_mfma_f32_16x16x32_bf16 v[52:55], v[164:167], v[190:193], 0
	v_mfma_f32_16x16x32_bf16 v[48:51], v[178:181], v[190:193], 0
	v_mfma_f32_16x16x32_bf16 v[36:39], v[164:167], v[198:201], 0
	v_mfma_f32_16x16x32_bf16 v[32:35], v[178:181], v[198:201], 0
	v_mfma_f32_16x16x32_bf16 v[20:23], v[164:167], v[206:209], 0
	v_mfma_f32_16x16x32_bf16 v[16:19], v[178:181], v[206:209], 0
	v_mfma_f32_16x16x32_bf16 v[4:7], v[164:167], v[214:217], 0
	v_mfma_f32_16x16x32_bf16 v[0:3], v[178:181], v[214:217], 0
	v_mfma_f32_16x16x32_bf16 v[52:55], v[168:171], v[194:197], v[52:55]
	v_mfma_f32_16x16x32_bf16 v[48:51], v[182:185], v[194:197], v[48:51]
	v_mfma_f32_16x16x32_bf16 v[36:39], v[168:171], v[202:205], v[36:39]
	v_mfma_f32_16x16x32_bf16 v[32:35], v[182:185], v[202:205], v[32:35]
	v_mfma_f32_16x16x32_bf16 v[20:23], v[168:171], v[210:213], v[20:23]
	v_mfma_f32_16x16x32_bf16 v[16:19], v[182:185], v[210:213], v[16:19]
	v_mfma_f32_16x16x32_bf16 v[4:7], v[168:171], v[218:221], v[4:7]
	v_mfma_f32_16x16x32_bf16 v[0:3], v[182:185], v[218:221], v[0:3]
	s_setprio 0
	s_barrier
	s_branch .Lmy_peel_882_mid
; #define PG8_STAGE(bufoff, gbase, voff) do { _Pragma("unroll") for (int _i = 0; _i < 2; ++_i) \
;         __builtin_amdgcn_global_load_lds((const unsigned*)((const char*)(gbase) + (voff)[_i]), (PG8_LAS unsigned*)(lds + (bufoff) + ldsw + _i * 8192), 16, 0, 0); } while (0)
; #define PG8_LDA(dst, b, h) do { _Pragma("unroll") for (int m = 0; m < 4; ++m) _Pragma("unroll") for (int k = 0; k < 2; ++k) dst[m][k] = *(const PG8_LAS bf16x8*)(lds + PG8_SA(b, h) + aoff + m * 2048 + k * 1024); } while (0)
; #define PG8_LDB(dst, b, h) do { _Pragma("unroll") for (int n = 0; n < 2; ++n) _Pragma("unroll") for (int k = 0; k < 2; ++k) dst[n][k] = *(const PG8_LAS bf16x8*)(lds + PG8_SB(b, h) + boff + n * 2048 + k * 1024); } while (0)
; #define PG8_MMA(ai, bj, At, Bt) do { __builtin_amdgcn_s_setprio(1); _Pragma("unroll") for (int m = 0; m < 4; ++m) _Pragma("unroll") for (int n = 0; n < 2; ++n) _Pragma("unroll") for (int k = 0; k < 2; ++k) \
;         acc[ai][bj][m][n] = __builtin_amdgcn_mfma_f32_16x16x32_bf16(Bt[n][k], At[m][k], acc[ai][bj][m][n], 0, 0, 0); __builtin_amdgcn_s_setprio(0); } while (0)
; #define PG8_WAIT_V(n) asm volatile("s_waitcnt vmcnt(" #n ")" ::: "memory")
; #define PG8_WAIT_L(n) asm volatile("s_waitcnt lgkmcnt(" #n ")" ::: "memory")
; #define PG8_BAR __builtin_amdgcn_s_barrier()
; #define PG8_SCHED __builtin_amdgcn_sched_barrier(0)
; template <class Epi, class Sched, bool ALIGN_EPI = false, bool SP2 = false>
; __device__ __forceinline__ void gemm_phase(PG8_LAS unsigned char* lds, const Gemm g, const Sched& S, const Epi& E) {
;     ...
;             PG8_LDB(B0, 0, 0); PG8_LDB(B1, 0, 1); PG8_SCHED; PG8_LDA(At, 0, 0); PG8_STAGE(PG8_SA(1, 1), a1 + hstep, voffA);
;             PG8_WAIT_V(8); PG8_WAIT_L(0); PG8_BAR; PG8_MMA(0, 0, At, B0); PG8_MMA(0, 1, At, B1); PG8_BAR; PG8_SCHED;
;             PG8_LDA(At, 0, 1); PG8_STAGE(PG8_SB(0, 0), b2, voffB); PG8_STAGE(PG8_SB(0, 1), b2 + hstep, voffB); PG8_STAGE(PG8_SA(0, 0), a2, voffA);
;             PG8_WAIT_V(8); PG8_WAIT_L(0); PG8_BAR; PG8_MMA(1, 0, At, B0); PG8_MMA(1, 1, At, B1); PG8_BAR; PG8_SCHED;
.LBB0_882:
	ds_read_b128 v[128:131], v173
	ds_read_b128 v[132:135], v173 offset:1024
	ds_read_b128 v[136:139], v173 offset:2048
	ds_read_b128 v[140:143], v173 offset:3072
	ds_read_b128 v[164:167], v174
	ds_read_b128 v[168:171], v174 offset:1024
	ds_read_b128 v[178:181], v174 offset:2048
	ds_read_b128 v[182:185], v174 offset:3072
	s_add_u32 s34, s30, 0xfffc0080
	s_addc_u32 s35, s31, -1
	s_cmp_eq_u32 s61, 12
	s_cselect_b32 s37, s23, s35
	s_cselect_b32 s36, s29, s34
	s_cselect_b32 s35, s21, s60
	s_cselect_b32 s34, s58, s59
	s_add_i32 m0, s43, 0xc000
	ds_read_b128 v[190:193], v175
	ds_read_b128 v[194:197], v175 offset:1024
	ds_read_b128 v[198:201], v175 offset:2048
	ds_read_b128 v[202:205], v175 offset:3072
	ds_read_b128 v[206:209], v175 offset:4096
	ds_read_b128 v[210:213], v175 offset:5120
	ds_read_b128 v[214:217], v175 offset:6144
	ds_read_b128 v[218:221], v175 offset:7168
	global_load_lds_dwordx4 v156, s[30:31]
	s_add_i32 m0, s43, 0xe000
	s_nop 0
	global_load_lds_dwordx4 v158, s[30:31]
	s_waitcnt vmcnt(8)
	s_waitcnt lgkmcnt(0)
	s_barrier
	s_setprio 1
	v_mfma_f32_16x16x32_bf16 v[124:127], v[128:131], v[190:193], v[124:127]
	v_mfma_f32_16x16x32_bf16 v[120:123], v[136:139], v[190:193], v[120:123]
	v_mfma_f32_16x16x32_bf16 v[108:111], v[128:131], v[198:201], v[108:111]
	v_mfma_f32_16x16x32_bf16 v[104:107], v[136:139], v[198:201], v[104:107]
	v_mfma_f32_16x16x32_bf16 v[92:95], v[128:131], v[206:209], v[92:95]
	v_mfma_f32_16x16x32_bf16 v[88:91], v[136:139], v[206:209], v[88:91]
	v_mfma_f32_16x16x32_bf16 v[76:79], v[128:131], v[214:217], v[76:79]
	v_mfma_f32_16x16x32_bf16 v[72:75], v[136:139], v[214:217], v[72:75]
	v_mfma_f32_16x16x32_bf16 v[124:127], v[132:135], v[194:197], v[124:127]
	v_mfma_f32_16x16x32_bf16 v[120:123], v[140:143], v[194:197], v[120:123]
	v_mfma_f32_16x16x32_bf16 v[108:111], v[132:135], v[202:205], v[108:111]
	v_mfma_f32_16x16x32_bf16 v[104:107], v[140:143], v[202:205], v[104:107]
	v_mfma_f32_16x16x32_bf16 v[92:95], v[132:135], v[210:213], v[92:95]
	v_mfma_f32_16x16x32_bf16 v[88:91], v[140:143], v[210:213], v[88:91]
	v_mfma_f32_16x16x32_bf16 v[76:79], v[132:135], v[218:221], v[76:79]
	v_mfma_f32_16x16x32_bf16 v[72:75], v[140:143], v[218:221], v[72:75]
	v_mfma_f32_16x16x32_bf16 v[116:119], v[164:167], v[190:193], v[116:119]
	v_mfma_f32_16x16x32_bf16 v[112:115], v[178:181], v[190:193], v[112:115]
	v_mfma_f32_16x16x32_bf16 v[100:103], v[164:167], v[198:201], v[100:103]
	v_mfma_f32_16x16x32_bf16 v[96:99], v[178:181], v[198:201], v[96:99]
	v_mfma_f32_16x16x32_bf16 v[84:87], v[164:167], v[206:209], v[84:87]
	v_mfma_f32_16x16x32_bf16 v[80:83], v[178:181], v[206:209], v[80:83]
	v_mfma_f32_16x16x32_bf16 v[68:71], v[164:167], v[214:217], v[68:71]
	v_mfma_f32_16x16x32_bf16 v[64:67], v[178:181], v[214:217], v[64:67]
	v_mfma_f32_16x16x32_bf16 v[116:119], v[168:171], v[194:197], v[116:119]
	v_mfma_f32_16x16x32_bf16 v[112:115], v[182:185], v[194:197], v[112:115]
	v_mfma_f32_16x16x32_bf16 v[100:103], v[168:171], v[202:205], v[100:103]
	v_mfma_f32_16x16x32_bf16 v[96:99], v[182:185], v[202:205], v[96:99]
	v_mfma_f32_16x16x32_bf16 v[84:87], v[168:171], v[210:213], v[84:87]
	v_mfma_f32_16x16x32_bf16 v[80:83], v[182:185], v[210:213], v[80:83]
	v_mfma_f32_16x16x32_bf16 v[68:71], v[168:171], v[218:221], v[68:71]
	v_mfma_f32_16x16x32_bf16 v[64:67], v[182:185], v[218:221], v[64:67]
	s_setprio 0
	s_barrier
	s_add_u32 s92, s34, s16
	s_addc_u32 s93, s35, s17
	s_add_u32 s94, s36, s16
	s_addc_u32 s95, s37, s17
	s_add_i32 s62, s55, s42
	s_mov_b32 m0, s62
	ds_read_b128 v[190:193], v175 offset:16384
	ds_read_b128 v[194:197], v175 offset:17408
	ds_read_b128 v[198:201], v175 offset:18432
	ds_read_b128 v[202:205], v175 offset:19456
	ds_read_b128 v[206:209], v175 offset:20480
	ds_read_b128 v[210:213], v175 offset:21504
	ds_read_b128 v[214:217], v175 offset:22528
	ds_read_b128 v[218:221], v175 offset:23552
	global_load_lds_dwordx4 v146, s[34:35]
	s_add_i32 m0, s62, 0x2000
	s_add_u32 s62, s34, 0x40000
	s_addc_u32 s63, s35, 0
	s_add_i32 s64, s56, s42
	global_load_lds_dwordx4 v150, s[34:35]
	s_mov_b32 m0, s64
	s_nop 0
	global_load_lds_dwordx4 v146, s[62:63]
	s_add_i32 m0, s64, 0x2000
	s_nop 0
	global_load_lds_dwordx4 v150, s[62:63]
	s_mov_b32 m0, s43
	s_nop 0
	global_load_lds_dwordx4 v144, s[36:37]
	s_mov_b32 m0, s44
	s_nop 0
	global_load_lds_dwordx4 v148, s[36:37]
	s_waitcnt vmcnt(8)
	s_waitcnt lgkmcnt(0)
	s_barrier
	s_setprio 1
	v_mfma_f32_16x16x32_bf16 v[60:63], v[128:131], v[190:193], v[60:63]
	v_mfma_f32_16x16x32_bf16 v[56:59], v[136:139], v[190:193], v[56:59]
	v_mfma_f32_16x16x32_bf16 v[44:47], v[128:131], v[198:201], v[44:47]
	v_mfma_f32_16x16x32_bf16 v[40:43], v[136:139], v[198:201], v[40:43]
	v_mfma_f32_16x16x32_bf16 v[28:31], v[128:131], v[206:209], v[28:31]
	v_mfma_f32_16x16x32_bf16 v[24:27], v[136:139], v[206:209], v[24:27]
	v_mfma_f32_16x16x32_bf16 v[12:15], v[128:131], v[214:217], v[12:15]
	v_mfma_f32_16x16x32_bf16 v[8:11], v[136:139], v[214:217], v[8:11]
	v_mfma_f32_16x16x32_bf16 v[60:63], v[132:135], v[194:197], v[60:63]
	v_mfma_f32_16x16x32_bf16 v[56:59], v[140:143], v[194:197], v[56:59]
	v_mfma_f32_16x16x32_bf16 v[44:47], v[132:135], v[202:205], v[44:47]
	v_mfma_f32_16x16x32_bf16 v[40:43], v[140:143], v[202:205], v[40:43]
	v_mfma_f32_16x16x32_bf16 v[28:31], v[132:135], v[210:213], v[28:31]
	v_mfma_f32_16x16x32_bf16 v[24:27], v[140:143], v[210:213], v[24:27]
	v_mfma_f32_16x16x32_bf16 v[12:15], v[132:135], v[218:221], v[12:15]
	v_mfma_f32_16x16x32_bf16 v[8:11], v[140:143], v[218:221], v[8:11]
	v_mfma_f32_16x16x32_bf16 v[52:55], v[164:167], v[190:193], v[52:55]
	v_mfma_f32_16x16x32_bf16 v[48:51], v[178:181], v[190:193], v[48:51]
	v_mfma_f32_16x16x32_bf16 v[36:39], v[164:167], v[198:201], v[36:39]
	v_mfma_f32_16x16x32_bf16 v[32:35], v[178:181], v[198:201], v[32:35]
	v_mfma_f32_16x16x32_bf16 v[20:23], v[164:167], v[206:209], v[20:23]
	v_mfma_f32_16x16x32_bf16 v[16:19], v[178:181], v[206:209], v[16:19]
	v_mfma_f32_16x16x32_bf16 v[4:7], v[164:167], v[214:217], v[4:7]
	v_mfma_f32_16x16x32_bf16 v[0:3], v[178:181], v[214:217], v[0:3]
	v_mfma_f32_16x16x32_bf16 v[52:55], v[168:171], v[194:197], v[52:55]
	v_mfma_f32_16x16x32_bf16 v[48:51], v[182:185], v[194:197], v[48:51]
	v_mfma_f32_16x16x32_bf16 v[36:39], v[168:171], v[202:205], v[36:39]
	v_mfma_f32_16x16x32_bf16 v[32:35], v[182:185], v[202:205], v[32:35]
	v_mfma_f32_16x16x32_bf16 v[20:23], v[168:171], v[210:213], v[20:23]
	v_mfma_f32_16x16x32_bf16 v[16:19], v[182:185], v[210:213], v[16:19]
	v_mfma_f32_16x16x32_bf16 v[4:7], v[168:171], v[218:221], v[4:7]
	v_mfma_f32_16x16x32_bf16 v[0:3], v[182:185], v[218:221], v[0:3]
	s_setprio 0
	s_barrier
; #define PG8_STAGE(bufoff, gbase, voff) do { _Pragma("unroll") for (int _i = 0; _i < 2; ++_i) \
;         __builtin_amdgcn_global_load_lds((const unsigned*)((const char*)(gbase) + (voff)[_i]), (PG8_LAS unsigned*)(lds + (bufoff) + ldsw + _i * 8192), 16, 0, 0); } while (0)
; #define PG8_LDA(dst, b, h) do { _Pragma("unroll") for (int m = 0; m < 4; ++m) _Pragma("unroll") for (int k = 0; k < 2; ++k) dst[m][k] = *(const PG8_LAS bf16x8*)(lds + PG8_SA(b, h) + aoff + m * 2048 + k * 1024); } while (0)
; #define PG8_LDB(dst, b, h) do { _Pragma("unroll") for (int n = 0; n < 2; ++n) _Pragma("unroll") for (int k = 0; k < 2; ++k) dst[n][k] = *(const PG8_LAS bf16x8*)(lds + PG8_SB(b, h) + boff + n * 2048 + k * 1024); } while (0)
; #define PG8_MMA(ai, bj, At, Bt) do { __builtin_amdgcn_s_setprio(1); _Pragma("unroll") for (int m = 0; m < 4; ++m) _Pragma("unroll") for (int n = 0; n < 2; ++n) _Pragma("unroll") for (int k = 0; k < 2; ++k) \
;         acc[ai][bj][m][n] = __builtin_amdgcn_mfma_f32_16x16x32_bf16(Bt[n][k], At[m][k], acc[ai][bj][m][n], 0, 0, 0); __builtin_amdgcn_s_setprio(0); } while (0)
; #define PG8_WAIT_V(n) asm volatile("s_waitcnt vmcnt(" #n ")" ::: "memory")
; #define PG8_WAIT_L(n) asm volatile("s_waitcnt lgkmcnt(" #n ")" ::: "memory")
; #define PG8_BAR __builtin_amdgcn_s_barrier()
; #define PG8_SCHED __builtin_amdgcn_sched_barrier(0)
; template <class Epi, class Sched, bool ALIGN_EPI = false, bool SP2 = false>
; __device__ __forceinline__ void gemm_phase(PG8_LAS unsigned char* lds, const Gemm g, const Sched& S, const Epi& E) {
;     ...
;             PG8_LDB(B0, 1, 0); PG8_LDB(B1, 1, 1); PG8_SCHED; PG8_LDA(At, 1, 0); PG8_STAGE(PG8_SA(0, 1), a2 + hstep, voffA);
;             PG8_WAIT_V(8); PG8_WAIT_L(0); PG8_BAR; PG8_MMA(0, 0, At, B0); PG8_MMA(0, 1, At, B1); PG8_BAR; PG8_SCHED;
;             PG8_LDA(At, 1, 1); PG8_STAGE(PG8_SB(1, 0), b3, voffB); PG8_STAGE(PG8_SB(1, 1), b3 + hstep, voffB); PG8_STAGE(PG8_SA(1, 0), a3, voffA);
;             PG8_WAIT_V(8); PG8_WAIT_L(0); PG8_BAR; PG8_MMA(1, 0, At, B0); PG8_MMA(1, 1, At, B1); PG8_BAR; PG8_SCHED;
.Lmy_peel_882_mid:
	s_add_i32 s62, 0, 0x18000
	s_add_i32 s63, 0, 0x1c000
	v_add_u32_e32 v140, s62, v172
	v_add_u32_e32 v177, s63, v172
	ds_read_b128 v[128:131], v140
	ds_read_b128 v[132:135], v140 offset:1024
	ds_read_b128 v[136:139], v140 offset:2048
	ds_read_b128 v[140:143], v140 offset:3072
	ds_read_b128 v[164:167], v177
	ds_read_b128 v[168:171], v177 offset:1024
	ds_read_b128 v[178:181], v177 offset:2048
	ds_read_b128 v[182:185], v177 offset:3072
	s_add_u32 s36, s36, 0x40000
	s_addc_u32 s37, s37, 0
	s_mov_b32 m0, s45
	ds_read_b128 v[190:193], v175 offset:32768
	ds_read_b128 v[194:197], v175 offset:33792
	ds_read_b128 v[198:201], v175 offset:34816
	ds_read_b128 v[202:205], v175 offset:35840
	ds_read_b128 v[206:209], v175 offset:36864
	ds_read_b128 v[210:213], v175 offset:37888
	ds_read_b128 v[214:217], v175 offset:38912
	ds_read_b128 v[218:221], v175 offset:39936
	global_load_lds_dwordx4 v144, s[36:37]
	s_mov_b32 m0, s46
	s_nop 0
	global_load_lds_dwordx4 v148, s[36:37]
	s_waitcnt vmcnt(8)
	s_waitcnt lgkmcnt(0)
	s_barrier
	s_setprio 1
	v_mfma_f32_16x16x32_bf16 v[124:127], v[128:131], v[190:193], v[124:127]
	v_mfma_f32_16x16x32_bf16 v[120:123], v[136:139], v[190:193], v[120:123]
	v_mfma_f32_16x16x32_bf16 v[108:111], v[128:131], v[198:201], v[108:111]
	v_mfma_f32_16x16x32_bf16 v[104:107], v[136:139], v[198:201], v[104:107]
	v_mfma_f32_16x16x32_bf16 v[92:95], v[128:131], v[206:209], v[92:95]
	v_mfma_f32_16x16x32_bf16 v[88:91], v[136:139], v[206:209], v[88:91]
	v_mfma_f32_16x16x32_bf16 v[76:79], v[128:131], v[214:217], v[76:79]
	v_mfma_f32_16x16x32_bf16 v[72:75], v[136:139], v[214:217], v[72:75]
	v_mfma_f32_16x16x32_bf16 v[124:127], v[132:135], v[194:197], v[124:127]
	v_mfma_f32_16x16x32_bf16 v[120:123], v[140:143], v[194:197], v[120:123]
	v_mfma_f32_16x16x32_bf16 v[108:111], v[132:135], v[202:205], v[108:111]
	v_mfma_f32_16x16x32_bf16 v[104:107], v[140:143], v[202:205], v[104:107]
	v_mfma_f32_16x16x32_bf16 v[92:95], v[132:135], v[210:213], v[92:95]
	v_mfma_f32_16x16x32_bf16 v[88:91], v[140:143], v[210:213], v[88:91]
	v_mfma_f32_16x16x32_bf16 v[76:79], v[132:135], v[218:221], v[76:79]
	v_mfma_f32_16x16x32_bf16 v[72:75], v[140:143], v[218:221], v[72:75]
	v_mfma_f32_16x16x32_bf16 v[116:119], v[164:167], v[190:193], v[116:119]
	v_mfma_f32_16x16x32_bf16 v[112:115], v[178:181], v[190:193], v[112:115]
	v_mfma_f32_16x16x32_bf16 v[100:103], v[164:167], v[198:201], v[100:103]
	v_mfma_f32_16x16x32_bf16 v[96:99], v[178:181], v[198:201], v[96:99]
	v_mfma_f32_16x16x32_bf16 v[84:87], v[164:167], v[206:209], v[84:87]
	v_mfma_f32_16x16x32_bf16 v[80:83], v[178:181], v[206:209], v[80:83]
	v_mfma_f32_16x16x32_bf16 v[68:71], v[164:167], v[214:217], v[68:71]
	v_mfma_f32_16x16x32_bf16 v[64:67], v[178:181], v[214:217], v[64:67]
	v_mfma_f32_16x16x32_bf16 v[116:119], v[168:171], v[194:197], v[116:119]
	v_mfma_f32_16x16x32_bf16 v[112:115], v[182:185], v[194:197], v[112:115]
	v_mfma_f32_16x16x32_bf16 v[100:103], v[168:171], v[202:205], v[100:103]
	v_mfma_f32_16x16x32_bf16 v[96:99], v[182:185], v[202:205], v[96:99]
	v_mfma_f32_16x16x32_bf16 v[84:87], v[168:171], v[210:213], v[84:87]
	v_mfma_f32_16x16x32_bf16 v[80:83], v[182:185], v[210:213], v[80:83]
	v_mfma_f32_16x16x32_bf16 v[68:71], v[168:171], v[218:221], v[68:71]
	v_mfma_f32_16x16x32_bf16 v[64:67], v[182:185], v[218:221], v[64:67]
	s_setprio 0
	s_barrier
	s_add_i32 s36, s62, s42
	s_mov_b32 m0, s36
	ds_read_b128 v[190:193], v175 offset:49152
	ds_read_b128 v[194:197], v175 offset:50176
	ds_read_b128 v[198:201], v175 offset:51200
	ds_read_b128 v[202:205], v175 offset:52224
	ds_read_b128 v[206:209], v175 offset:53248
	ds_read_b128 v[210:213], v175 offset:54272
	ds_read_b128 v[214:217], v175 offset:55296
	ds_read_b128 v[218:221], v175 offset:56320
	global_load_lds_dwordx4 v146, s[92:93]
	s_add_i32 m0, s36, 0x2000
	s_add_u32 s34, s34, 0x40080
	s_addc_u32 s35, s35, 0
	s_add_i32 s36, s63, s42
	global_load_lds_dwordx4 v150, s[92:93]
	s_mov_b32 m0, s36
	s_nop 0
	global_load_lds_dwordx4 v146, s[34:35]
	s_add_i32 m0, s36, 0x2000
	s_nop 0
	global_load_lds_dwordx4 v150, s[34:35]
	s_mov_b32 m0, s48
	s_nop 0
	global_load_lds_dwordx4 v144, s[94:95]
	s_mov_b32 m0, s49
	s_nop 0
	global_load_lds_dwordx4 v148, s[94:95]
	s_waitcnt vmcnt(8)
	s_waitcnt lgkmcnt(0)
	s_barrier
	s_setprio 1
	v_mfma_f32_16x16x32_bf16 v[60:63], v[128:131], v[190:193], v[60:63]
	v_mfma_f32_16x16x32_bf16 v[56:59], v[136:139], v[190:193], v[56:59]
	v_mfma_f32_16x16x32_bf16 v[44:47], v[128:131], v[198:201], v[44:47]
	v_mfma_f32_16x16x32_bf16 v[40:43], v[136:139], v[198:201], v[40:43]
	v_mfma_f32_16x16x32_bf16 v[28:31], v[128:131], v[206:209], v[28:31]
	v_mfma_f32_16x16x32_bf16 v[24:27], v[136:139], v[206:209], v[24:27]
	v_mfma_f32_16x16x32_bf16 v[12:15], v[128:131], v[214:217], v[12:15]
	v_mfma_f32_16x16x32_bf16 v[8:11], v[136:139], v[214:217], v[8:11]
	v_mfma_f32_16x16x32_bf16 v[60:63], v[132:135], v[194:197], v[60:63]
	v_mfma_f32_16x16x32_bf16 v[56:59], v[140:143], v[194:197], v[56:59]
	v_mfma_f32_16x16x32_bf16 v[44:47], v[132:135], v[202:205], v[44:47]
	v_mfma_f32_16x16x32_bf16 v[40:43], v[140:143], v[202:205], v[40:43]
	v_mfma_f32_16x16x32_bf16 v[28:31], v[132:135], v[210:213], v[28:31]
	v_mfma_f32_16x16x32_bf16 v[24:27], v[140:143], v[210:213], v[24:27]
	v_mfma_f32_16x16x32_bf16 v[12:15], v[132:135], v[218:221], v[12:15]
	v_mfma_f32_16x16x32_bf16 v[8:11], v[140:143], v[218:221], v[8:11]
	v_mfma_f32_16x16x32_bf16 v[52:55], v[164:167], v[190:193], v[52:55]
	v_mfma_f32_16x16x32_bf16 v[48:51], v[178:181], v[190:193], v[48:51]
	v_mfma_f32_16x16x32_bf16 v[36:39], v[164:167], v[198:201], v[36:39]
	v_mfma_f32_16x16x32_bf16 v[32:35], v[178:181], v[198:201], v[32:35]
	v_mfma_f32_16x16x32_bf16 v[20:23], v[164:167], v[206:209], v[20:23]
	v_mfma_f32_16x16x32_bf16 v[16:19], v[178:181], v[206:209], v[16:19]
	v_mfma_f32_16x16x32_bf16 v[4:7], v[164:167], v[214:217], v[4:7]
	v_mfma_f32_16x16x32_bf16 v[0:3], v[178:181], v[214:217], v[0:3]
	v_mfma_f32_16x16x32_bf16 v[52:55], v[168:171], v[194:197], v[52:55]
	v_mfma_f32_16x16x32_bf16 v[48:51], v[182:185], v[194:197], v[48:51]
	v_mfma_f32_16x16x32_bf16 v[36:39], v[168:171], v[202:205], v[36:39]
	v_mfma_f32_16x16x32_bf16 v[32:35], v[182:185], v[202:205], v[32:35]
	v_mfma_f32_16x16x32_bf16 v[20:23], v[168:171], v[210:213], v[20:23]
	v_mfma_f32_16x16x32_bf16 v[16:19], v[182:185], v[210:213], v[16:19]
	v_mfma_f32_16x16x32_bf16 v[4:7], v[168:171], v[218:221], v[4:7]
	v_mfma_f32_16x16x32_bf16 v[0:3], v[182:185], v[218:221], v[0:3]
	s_setprio 0
	s_barrier
	s_add_i32 s61, s61, 2
	s_add_u32 s30, s30, 0x100
	s_addc_u32 s31, s31, 0
	s_add_u32 s59, s59, 0x100
	s_addc_u32 s60, s60, 0
	s_cmp_gt_u32 s61, 13
	s_cbranch_scc0 .LBB0_882
	s_and_b64 vcc, exec, s[18:19]
	s_cbranch_vccz .LBB0_885
	s_barrier

; #define PG8_STAGE(bufoff, gbase, voff) do { _Pragma("unroll") for (int _i = 0; _i < 2; ++_i) \
;         __builtin_amdgcn_global_load_lds((const unsigned*)((const char*)(gbase) + (voff)[_i]), (PG8_LAS unsigned*)(lds + (bufoff) + ldsw + _i * 8192), 16, 0, 0); } while (0)
; #define PG8_LDA(dst, b, h) do { _Pragma("unroll") for (int m = 0; m < 4; ++m) _Pragma("unroll") for (int k = 0; k < 2; ++k) dst[m][k] = *(const PG8_LAS bf16x8*)(lds + PG8_SA(b, h) + aoff + m * 2048 + k * 1024); } while (0)
; #define PG8_LDB(dst, b, h) do { _Pragma("unroll") for (int n = 0; n < 2; ++n) _Pragma("unroll") for (int k = 0; k < 2; ++k) dst[n][k] = *(const PG8_LAS bf16x8*)(lds + PG8_SB(b, h) + boff + n * 2048 + k * 1024); } while (0)
; #define PG8_MMA(ai, bj, At, Bt) do { __builtin_amdgcn_s_setprio(1); _Pragma("unroll") for (int m = 0; m < 4; ++m) _Pragma("unroll") for (int n = 0; n < 2; ++n) _Pragma("unroll") for (int k = 0; k < 2; ++k) \
;         acc[ai][bj][m][n] = __builtin_amdgcn_mfma_f32_16x16x32_bf16(Bt[n][k], At[m][k], acc[ai][bj][m][n], 0, 0, 0); __builtin_amdgcn_s_setprio(0); } while (0)
; #define PG8_WAIT_V(n) asm volatile("s_waitcnt vmcnt(" #n ")" ::: "memory")
; #define PG8_WAIT_L(n) asm volatile("s_waitcnt lgkmcnt(" #n ")" ::: "memory")
; template <class Epi, class Sched, bool ALIGN_EPI = false, bool SP2 = false>
; __device__ __forceinline__ void gemm_phase(PG8_LAS unsigned char* lds, const Gemm g, const Sched& S, const Epi& E) {
;     ...
;             const bool last = (t == nt - 2);
;             const char* a1 = cA + (size_t)(t + 1) * kstep;
;             const char* a2 = last ? nA : cA + (size_t)(t + 2) * kstep; const char* b2 = last ? nB : cB + (size_t)(t + 2) * kstep;
;             const char* a3 = a2 + kstep; const char* b3 = b2 + kstep;
;             if (last && has_next) S.a_ready(nxt);
;             if constexpr (SP2) {
;             PG8_LDB(B0, 0, 0); PG8_LDB(B1, 0, 1); PG8_SCHED; PG8_LDA(At, 0, 0); PG8_STAGE(PG8_SA(1, 1), a1 + hstep, voffA);
;             PG8_WAIT_V(8); PG8_WAIT_L(0); PG8_BAR; PG8_MMA(0, 0, At, B0); PG8_MMA(0, 1, At, B1); PG8_BAR; PG8_SCHED;
;             PG8_LDA(At, 0, 1); PG8_STAGE(PG8_SB(0, 0), b2, voffB); PG8_STAGE(PG8_SB(0, 1), b2 + hstep, voffB); PG8_STAGE(PG8_SA(0, 0), a2, voffA);
;             PG8_WAIT_V(8); PG8_WAIT_L(0); PG8_BAR; PG8_MMA(1, 0, At, B0); PG8_MMA(1, 1, At, B1); PG8_BAR; PG8_SCHED;
.LBB0_968:
	s_ashr_i32 s17, s16, 31
	s_lshl_b64 s[18:19], s[16:17], 19
	s_add_u32 s18, s30, s18
	s_addc_u32 s19, s31, s19
	s_and_b64 s[20:21], s[2:3], exec
	s_cselect_b32 s17, s19, s25
	s_cselect_b32 s51, s18, s24
	s_ashr_i32 s15, s14, 31
	s_lshl_b64 s[20:21], s[14:15], 19
	s_add_u32 s20, s34, s20
	s_addc_u32 s21, s35, s21
	s_and_b64 s[28:29], s[2:3], exec
	s_cselect_b32 s15, s21, s27
	s_cselect_b32 s54, s20, s26
	s_add_u32 s24, s24, 0x40080
	s_addc_u32 s25, s25, 0
	s_add_u32 s55, s26, 0x100
	s_addc_u32 s56, s27, 0
	s_mov_b32 s57, -2
	ds_read_b128 v[128:131], v191
	ds_read_b128 v[132:135], v191 offset:1024
	ds_read_b128 v[136:139], v191 offset:2048
	ds_read_b128 v[140:143], v191 offset:3072
	ds_read_b128 v[144:147], v192
	ds_read_b128 v[148:151], v192 offset:1024
	ds_read_b128 v[172:175], v192 offset:2048
	ds_read_b128 v[176:179], v192 offset:3072
	s_add_u32 s26, s24, 0xfffc0080
	s_addc_u32 s27, s25, -1
	s_cmp_eq_u32 s57, 12
	s_cselect_b32 s29, s17, s27
	s_cselect_b32 s28, s51, s26
	s_cselect_b32 s27, s15, s56
	s_cselect_b32 s26, s54, s55
	s_add_i32 m0, s39, 0xc000
	ds_read_b128 v[180:183], v193
	ds_read_b128 v[184:187], v193 offset:1024
	ds_read_b128 v[196:199], v193 offset:2048
	ds_read_b128 v[200:203], v193 offset:3072
	ds_read_b128 v[204:207], v193 offset:4096
	ds_read_b128 v[208:211], v193 offset:5120
	ds_read_b128 v[212:215], v193 offset:6144
	ds_read_b128 v[216:219], v193 offset:7168
	global_load_lds_dwordx4 v164, s[24:25]
	s_add_i32 m0, s39, 0xe000
	s_nop 0
	global_load_lds_dwordx4 v166, s[24:25]
	s_waitcnt vmcnt(8)
	s_waitcnt lgkmcnt(0)
	s_barrier
	s_setprio 1
	v_mfma_f32_16x16x32_bf16 v[124:127], v[128:131], v[180:183], 0
	v_mfma_f32_16x16x32_bf16 v[120:123], v[136:139], v[180:183], 0
	v_mfma_f32_16x16x32_bf16 v[108:111], v[128:131], v[196:199], 0
	v_mfma_f32_16x16x32_bf16 v[104:107], v[136:139], v[196:199], 0
	v_mfma_f32_16x16x32_bf16 v[92:95], v[128:131], v[204:207], 0
	v_mfma_f32_16x16x32_bf16 v[84:87], v[136:139], v[204:207], 0
	v_mfma_f32_16x16x32_bf16 v[76:79], v[128:131], v[212:215], 0
	v_mfma_f32_16x16x32_bf16 v[72:75], v[136:139], v[212:215], 0
	v_mfma_f32_16x16x32_bf16 v[124:127], v[132:135], v[184:187], v[124:127]
	v_mfma_f32_16x16x32_bf16 v[120:123], v[140:143], v[184:187], v[120:123]
	v_mfma_f32_16x16x32_bf16 v[108:111], v[132:135], v[200:203], v[108:111]
	v_mfma_f32_16x16x32_bf16 v[104:107], v[140:143], v[200:203], v[104:107]
	v_mfma_f32_16x16x32_bf16 v[92:95], v[132:135], v[208:211], v[92:95]
	v_mfma_f32_16x16x32_bf16 v[84:87], v[140:143], v[208:211], v[84:87]
	v_mfma_f32_16x16x32_bf16 v[76:79], v[132:135], v[216:219], v[76:79]
	v_mfma_f32_16x16x32_bf16 v[72:75], v[140:143], v[216:219], v[72:75]
	v_mfma_f32_16x16x32_bf16 v[116:119], v[144:147], v[180:183], 0
	v_mfma_f32_16x16x32_bf16 v[112:115], v[172:175], v[180:183], 0
	v_mfma_f32_16x16x32_bf16 v[100:103], v[144:147], v[196:199], 0
	v_mfma_f32_16x16x32_bf16 v[96:99], v[172:175], v[196:199], 0
	v_mfma_f32_16x16x32_bf16 v[88:91], v[144:147], v[204:207], 0
	v_mfma_f32_16x16x32_bf16 v[80:83], v[172:175], v[204:207], 0
	v_mfma_f32_16x16x32_bf16 v[68:71], v[144:147], v[212:215], 0
	v_mfma_f32_16x16x32_bf16 v[64:67], v[172:175], v[212:215], 0
	v_mfma_f32_16x16x32_bf16 v[116:119], v[148:151], v[184:187], v[116:119]
	v_mfma_f32_16x16x32_bf16 v[112:115], v[176:179], v[184:187], v[112:115]
	v_mfma_f32_16x16x32_bf16 v[100:103], v[148:151], v[200:203], v[100:103]
	v_mfma_f32_16x16x32_bf16 v[96:99], v[176:179], v[200:203], v[96:99]
	v_mfma_f32_16x16x32_bf16 v[88:91], v[148:151], v[208:211], v[88:91]
	v_mfma_f32_16x16x32_bf16 v[80:83], v[176:179], v[208:211], v[80:83]
	v_mfma_f32_16x16x32_bf16 v[68:71], v[148:151], v[216:219], v[68:71]
	v_mfma_f32_16x16x32_bf16 v[64:67], v[176:179], v[216:219], v[64:67]
	s_setprio 0
	s_barrier
	s_add_u32 s92, s26, s10
	s_addc_u32 s93, s27, s11
	s_add_u32 s94, s28, s10
	s_addc_u32 s95, s29, s11
	s_add_i32 s58, s47, s36
	s_mov_b32 m0, s58
	ds_read_b128 v[180:183], v193 offset:16384
	ds_read_b128 v[184:187], v193 offset:17408
	ds_read_b128 v[196:199], v193 offset:18432
	ds_read_b128 v[200:203], v193 offset:19456
	ds_read_b128 v[204:207], v193 offset:20480
	ds_read_b128 v[208:211], v193 offset:21504
	ds_read_b128 v[212:215], v193 offset:22528
	ds_read_b128 v[216:219], v193 offset:23552
	global_load_lds_dwordx4 v156, s[26:27]
	s_add_i32 m0, s58, 0x2000
	s_add_u32 s58, s26, 0x40000
	s_addc_u32 s59, s27, 0
	s_add_i32 s60, s48, s36
	global_load_lds_dwordx4 v152, s[26:27]
	s_mov_b32 m0, s60
	s_nop 0
	global_load_lds_dwordx4 v156, s[58:59]
	s_add_i32 m0, s60, 0x2000
	s_nop 0
	global_load_lds_dwordx4 v152, s[58:59]
	s_mov_b32 m0, s39
	s_nop 0
	global_load_lds_dwordx4 v158, s[28:29]
	s_mov_b32 m0, s40
	s_nop 0
	global_load_lds_dwordx4 v154, s[28:29]
	s_waitcnt vmcnt(8)
	s_waitcnt lgkmcnt(0)
	s_barrier
	s_setprio 1
	v_mfma_f32_16x16x32_bf16 v[60:63], v[128:131], v[180:183], 0
	v_mfma_f32_16x16x32_bf16 v[52:55], v[136:139], v[180:183], 0
	v_mfma_f32_16x16x32_bf16 v[44:47], v[128:131], v[196:199], 0
	v_mfma_f32_16x16x32_bf16 v[40:43], v[136:139], v[196:199], 0
	v_mfma_f32_16x16x32_bf16 v[28:31], v[128:131], v[204:207], 0
	v_mfma_f32_16x16x32_bf16 v[20:23], v[136:139], v[204:207], 0
	v_mfma_f32_16x16x32_bf16 v[12:15], v[128:131], v[212:215], 0
	v_mfma_f32_16x16x32_bf16 v[8:11], v[136:139], v[212:215], 0
	v_mfma_f32_16x16x32_bf16 v[60:63], v[132:135], v[184:187], v[60:63]
	v_mfma_f32_16x16x32_bf16 v[52:55], v[140:143], v[184:187], v[52:55]
	v_mfma_f32_16x16x32_bf16 v[44:47], v[132:135], v[200:203], v[44:47]
	v_mfma_f32_16x16x32_bf16 v[40:43], v[140:143], v[200:203], v[40:43]
	v_mfma_f32_16x16x32_bf16 v[28:31], v[132:135], v[208:211], v[28:31]
	v_mfma_f32_16x16x32_bf16 v[20:23], v[140:143], v[208:211], v[20:23]
	v_mfma_f32_16x16x32_bf16 v[12:15], v[132:135], v[216:219], v[12:15]
	v_mfma_f32_16x16x32_bf16 v[8:11], v[140:143], v[216:219], v[8:11]
	v_mfma_f32_16x16x32_bf16 v[56:59], v[144:147], v[180:183], 0
	v_mfma_f32_16x16x32_bf16 v[48:51], v[172:175], v[180:183], 0
	v_mfma_f32_16x16x32_bf16 v[36:39], v[144:147], v[196:199], 0
	v_mfma_f32_16x16x32_bf16 v[32:35], v[172:175], v[196:199], 0
	v_mfma_f32_16x16x32_bf16 v[24:27], v[144:147], v[204:207], 0
	v_mfma_f32_16x16x32_bf16 v[16:19], v[172:175], v[204:207], 0
	v_mfma_f32_16x16x32_bf16 v[4:7], v[144:147], v[212:215], 0
	v_mfma_f32_16x16x32_bf16 v[0:3], v[172:175], v[212:215], 0
	v_mfma_f32_16x16x32_bf16 v[56:59], v[148:151], v[184:187], v[56:59]
	v_mfma_f32_16x16x32_bf16 v[48:51], v[176:179], v[184:187], v[48:51]
	v_mfma_f32_16x16x32_bf16 v[36:39], v[148:151], v[200:203], v[36:39]
	v_mfma_f32_16x16x32_bf16 v[32:35], v[176:179], v[200:203], v[32:35]
	v_mfma_f32_16x16x32_bf16 v[24:27], v[148:151], v[208:211], v[24:27]
	v_mfma_f32_16x16x32_bf16 v[16:19], v[176:179], v[208:211], v[16:19]
	v_mfma_f32_16x16x32_bf16 v[4:7], v[148:151], v[216:219], v[4:7]
	v_mfma_f32_16x16x32_bf16 v[0:3], v[176:179], v[216:219], v[0:3]
	s_setprio 0
	s_barrier
	s_branch .Lmy_peel_969_mid
; #define PG8_STAGE(bufoff, gbase, voff) do { _Pragma("unroll") for (int _i = 0; _i < 2; ++_i) \
;         __builtin_amdgcn_global_load_lds((const unsigned*)((const char*)(gbase) + (voff)[_i]), (PG8_LAS unsigned*)(lds + (bufoff) + ldsw + _i * 8192), 16, 0, 0); } while (0)
; #define PG8_LDA(dst, b, h) do { _Pragma("unroll") for (int m = 0; m < 4; ++m) _Pragma("unroll") for (int k = 0; k < 2; ++k) dst[m][k] = *(const PG8_LAS bf16x8*)(lds + PG8_SA(b, h) + aoff + m * 2048 + k * 1024); } while (0)
; #define PG8_LDB(dst, b, h) do { _Pragma("unroll") for (int n = 0; n < 2; ++n) _Pragma("unroll") for (int k = 0; k < 2; ++k) dst[n][k] = *(const PG8_LAS bf16x8*)(lds + PG8_SB(b, h) + boff + n * 2048 + k * 1024); } while (0)
; #define PG8_MMA(ai, bj, At, Bt) do { __builtin_amdgcn_s_setprio(1); _Pragma("unroll") for (int m = 0; m < 4; ++m) _Pragma("unroll") for (int n = 0; n < 2; ++n) _Pragma("unroll") for (int k = 0; k < 2; ++k) \
;         acc[ai][bj][m][n] = __builtin_amdgcn_mfma_f32_16x16x32_bf16(Bt[n][k], At[m][k], acc[ai][bj][m][n], 0, 0, 0); __builtin_amdgcn_s_setprio(0); } while (0)
; #define PG8_WAIT_V(n) asm volatile("s_waitcnt vmcnt(" #n ")" ::: "memory")
; #define PG8_WAIT_L(n) asm volatile("s_waitcnt lgkmcnt(" #n ")" ::: "memory")
; #define PG8_BAR __builtin_amdgcn_s_barrier()
; #define PG8_SCHED __builtin_amdgcn_sched_barrier(0)
; template <class Epi, class Sched, bool ALIGN_EPI = false, bool SP2 = false>
; __device__ __forceinline__ void gemm_phase(PG8_LAS unsigned char* lds, const Gemm g, const Sched& S, const Epi& E) {
;     ...
;             PG8_LDB(B0, 0, 0); PG8_LDB(B1, 0, 1); PG8_SCHED; PG8_LDA(At, 0, 0); PG8_STAGE(PG8_SA(1, 1), a1 + hstep, voffA);
;             PG8_WAIT_V(8); PG8_WAIT_L(0); PG8_BAR; PG8_MMA(0, 0, At, B0); PG8_MMA(0, 1, At, B1); PG8_BAR; PG8_SCHED;
;             PG8_LDA(At, 0, 1); PG8_STAGE(PG8_SB(0, 0), b2, voffB); PG8_STAGE(PG8_SB(0, 1), b2 + hstep, voffB); PG8_STAGE(PG8_SA(0, 0), a2, voffA);
;             PG8_WAIT_V(8); PG8_WAIT_L(0); PG8_BAR; PG8_MMA(1, 0, At, B0); PG8_MMA(1, 1, At, B1); PG8_BAR; PG8_SCHED;
.LBB0_969:
	ds_read_b128 v[128:131], v191
	ds_read_b128 v[132:135], v191 offset:1024
	ds_read_b128 v[136:139], v191 offset:2048
	ds_read_b128 v[140:143], v191 offset:3072
	ds_read_b128 v[144:147], v192
	ds_read_b128 v[148:151], v192 offset:1024
	ds_read_b128 v[172:175], v192 offset:2048
	ds_read_b128 v[176:179], v192 offset:3072
	s_add_u32 s26, s24, 0xfffc0080
	s_addc_u32 s27, s25, -1
	s_cmp_eq_u32 s57, 12
	s_cselect_b32 s29, s17, s27
	s_cselect_b32 s28, s51, s26
	s_cselect_b32 s27, s15, s56
	s_cselect_b32 s26, s54, s55
	s_add_i32 m0, s39, 0xc000
	ds_read_b128 v[180:183], v193
	ds_read_b128 v[184:187], v193 offset:1024
	ds_read_b128 v[196:199], v193 offset:2048
	ds_read_b128 v[200:203], v193 offset:3072
	ds_read_b128 v[204:207], v193 offset:4096
	ds_read_b128 v[208:211], v193 offset:5120
	ds_read_b128 v[212:215], v193 offset:6144
	ds_read_b128 v[216:219], v193 offset:7168
	global_load_lds_dwordx4 v164, s[24:25]
	s_add_i32 m0, s39, 0xe000
	s_nop 0
	global_load_lds_dwordx4 v166, s[24:25]
	s_waitcnt vmcnt(8)
	s_waitcnt lgkmcnt(0)
	s_barrier
	s_setprio 1
	v_mfma_f32_16x16x32_bf16 v[124:127], v[128:131], v[180:183], v[124:127]
	v_mfma_f32_16x16x32_bf16 v[120:123], v[136:139], v[180:183], v[120:123]
	v_mfma_f32_16x16x32_bf16 v[108:111], v[128:131], v[196:199], v[108:111]
	v_mfma_f32_16x16x32_bf16 v[104:107], v[136:139], v[196:199], v[104:107]
	v_mfma_f32_16x16x32_bf16 v[92:95], v[128:131], v[204:207], v[92:95]
	v_mfma_f32_16x16x32_bf16 v[84:87], v[136:139], v[204:207], v[84:87]
	v_mfma_f32_16x16x32_bf16 v[76:79], v[128:131], v[212:215], v[76:79]
	v_mfma_f32_16x16x32_bf16 v[72:75], v[136:139], v[212:215], v[72:75]
	v_mfma_f32_16x16x32_bf16 v[124:127], v[132:135], v[184:187], v[124:127]
	v_mfma_f32_16x16x32_bf16 v[120:123], v[140:143], v[184:187], v[120:123]
	v_mfma_f32_16x16x32_bf16 v[108:111], v[132:135], v[200:203], v[108:111]
	v_mfma_f32_16x16x32_bf16 v[104:107], v[140:143], v[200:203], v[104:107]
	v_mfma_f32_16x16x32_bf16 v[92:95], v[132:135], v[208:211], v[92:95]
	v_mfma_f32_16x16x32_bf16 v[84:87], v[140:143], v[208:211], v[84:87]
	v_mfma_f32_16x16x32_bf16 v[76:79], v[132:135], v[216:219], v[76:79]
	v_mfma_f32_16x16x32_bf16 v[72:75], v[140:143], v[216:219], v[72:75]
	v_mfma_f32_16x16x32_bf16 v[116:119], v[144:147], v[180:183], v[116:119]
	v_mfma_f32_16x16x32_bf16 v[112:115], v[172:175], v[180:183], v[112:115]
	v_mfma_f32_16x16x32_bf16 v[100:103], v[144:147], v[196:199], v[100:103]
	v_mfma_f32_16x16x32_bf16 v[96:99], v[172:175], v[196:199], v[96:99]
	v_mfma_f32_16x16x32_bf16 v[88:91], v[144:147], v[204:207], v[88:91]
	v_mfma_f32_16x16x32_bf16 v[80:83], v[172:175], v[204:207], v[80:83]
	v_mfma_f32_16x16x32_bf16 v[68:71], v[144:147], v[212:215], v[68:71]
	v_mfma_f32_16x16x32_bf16 v[64:67], v[172:175], v[212:215], v[64:67]
	v_mfma_f32_16x16x32_bf16 v[116:119], v[148:151], v[184:187], v[116:119]
	v_mfma_f32_16x16x32_bf16 v[112:115], v[176:179], v[184:187], v[112:115]
	v_mfma_f32_16x16x32_bf16 v[100:103], v[148:151], v[200:203], v[100:103]
	v_mfma_f32_16x16x32_bf16 v[96:99], v[176:179], v[200:203], v[96:99]
	v_mfma_f32_16x16x32_bf16 v[88:91], v[148:151], v[208:211], v[88:91]
	v_mfma_f32_16x16x32_bf16 v[80:83], v[176:179], v[208:211], v[80:83]
	v_mfma_f32_16x16x32_bf16 v[68:71], v[148:151], v[216:219], v[68:71]
	v_mfma_f32_16x16x32_bf16 v[64:67], v[176:179], v[216:219], v[64:67]
	s_setprio 0
	s_barrier
	s_add_u32 s92, s26, s10
	s_addc_u32 s93, s27, s11
	s_add_u32 s94, s28, s10
	s_addc_u32 s95, s29, s11
	s_add_i32 s58, s47, s36
	s_mov_b32 m0, s58
	ds_read_b128 v[180:183], v193 offset:16384
	ds_read_b128 v[184:187], v193 offset:17408
	ds_read_b128 v[196:199], v193 offset:18432
	ds_read_b128 v[200:203], v193 offset:19456
	ds_read_b128 v[204:207], v193 offset:20480
	ds_read_b128 v[208:211], v193 offset:21504
	ds_read_b128 v[212:215], v193 offset:22528
	ds_read_b128 v[216:219], v193 offset:23552
	global_load_lds_dwordx4 v156, s[26:27]
	s_add_i32 m0, s58, 0x2000
	s_add_u32 s58, s26, 0x40000
	s_addc_u32 s59, s27, 0
	s_add_i32 s60, s48, s36
	global_load_lds_dwordx4 v152, s[26:27]
	s_mov_b32 m0, s60
	s_nop 0
	global_load_lds_dwordx4 v156, s[58:59]
	s_add_i32 m0, s60, 0x2000
	s_nop 0
	global_load_lds_dwordx4 v152, s[58:59]
	s_mov_b32 m0, s39
	s_nop 0
	global_load_lds_dwordx4 v158, s[28:29]
	s_mov_b32 m0, s40
	s_nop 0
	global_load_lds_dwordx4 v154, s[28:29]
	s_waitcnt vmcnt(8)
	s_waitcnt lgkmcnt(0)
	s_barrier
	s_setprio 1
	v_mfma_f32_16x16x32_bf16 v[60:63], v[128:131], v[180:183], v[60:63]
	v_mfma_f32_16x16x32_bf16 v[52:55], v[136:139], v[180:183], v[52:55]
	v_mfma_f32_16x16x32_bf16 v[44:47], v[128:131], v[196:199], v[44:47]
	v_mfma_f32_16x16x32_bf16 v[40:43], v[136:139], v[196:199], v[40:43]
	v_mfma_f32_16x16x32_bf16 v[28:31], v[128:131], v[204:207], v[28:31]
	v_mfma_f32_16x16x32_bf16 v[20:23], v[136:139], v[204:207], v[20:23]
	v_mfma_f32_16x16x32_bf16 v[12:15], v[128:131], v[212:215], v[12:15]
	v_mfma_f32_16x16x32_bf16 v[8:11], v[136:139], v[212:215], v[8:11]
	v_mfma_f32_16x16x32_bf16 v[60:63], v[132:135], v[184:187], v[60:63]
	v_mfma_f32_16x16x32_bf16 v[52:55], v[140:143], v[184:187], v[52:55]
	v_mfma_f32_16x16x32_bf16 v[44:47], v[132:135], v[200:203], v[44:47]
	v_mfma_f32_16x16x32_bf16 v[40:43], v[140:143], v[200:203], v[40:43]
	v_mfma_f32_16x16x32_bf16 v[28:31], v[132:135], v[208:211], v[28:31]
	v_mfma_f32_16x16x32_bf16 v[20:23], v[140:143], v[208:211], v[20:23]
	v_mfma_f32_16x16x32_bf16 v[12:15], v[132:135], v[216:219], v[12:15]
	v_mfma_f32_16x16x32_bf16 v[8:11], v[140:143], v[216:219], v[8:11]
	v_mfma_f32_16x16x32_bf16 v[56:59], v[144:147], v[180:183], v[56:59]
	v_mfma_f32_16x16x32_bf16 v[48:51], v[172:175], v[180:183], v[48:51]
	v_mfma_f32_16x16x32_bf16 v[36:39], v[144:147], v[196:199], v[36:39]
	v_mfma_f32_16x16x32_bf16 v[32:35], v[172:175], v[196:199], v[32:35]
	v_mfma_f32_16x16x32_bf16 v[24:27], v[144:147], v[204:207], v[24:27]
	v_mfma_f32_16x16x32_bf16 v[16:19], v[172:175], v[204:207], v[16:19]
	v_mfma_f32_16x16x32_bf16 v[4:7], v[144:147], v[212:215], v[4:7]
	v_mfma_f32_16x16x32_bf16 v[0:3], v[172:175], v[212:215], v[0:3]
	v_mfma_f32_16x16x32_bf16 v[56:59], v[148:151], v[184:187], v[56:59]
	v_mfma_f32_16x16x32_bf16 v[48:51], v[176:179], v[184:187], v[48:51]
	v_mfma_f32_16x16x32_bf16 v[36:39], v[148:151], v[200:203], v[36:39]
	v_mfma_f32_16x16x32_bf16 v[32:35], v[176:179], v[200:203], v[32:35]
	v_mfma_f32_16x16x32_bf16 v[24:27], v[148:151], v[208:211], v[24:27]
	v_mfma_f32_16x16x32_bf16 v[16:19], v[176:179], v[208:211], v[16:19]
	v_mfma_f32_16x16x32_bf16 v[4:7], v[148:151], v[216:219], v[4:7]
	v_mfma_f32_16x16x32_bf16 v[0:3], v[176:179], v[216:219], v[0:3]
	s_setprio 0
	s_barrier
; #define PG8_STAGE(bufoff, gbase, voff) do { _Pragma("unroll") for (int _i = 0; _i < 2; ++_i) \
;         __builtin_amdgcn_global_load_lds((const unsigned*)((const char*)(gbase) + (voff)[_i]), (PG8_LAS unsigned*)(lds + (bufoff) + ldsw + _i * 8192), 16, 0, 0); } while (0)
; #define PG8_LDA(dst, b, h) do { _Pragma("unroll") for (int m = 0; m < 4; ++m) _Pragma("unroll") for (int k = 0; k < 2; ++k) dst[m][k] = *(const PG8_LAS bf16x8*)(lds + PG8_SA(b, h) + aoff + m * 2048 + k * 1024); } while (0)
; #define PG8_LDB(dst, b, h) do { _Pragma("unroll") for (int n = 0; n < 2; ++n) _Pragma("unroll") for (int k = 0; k < 2; ++k) dst[n][k] = *(const PG8_LAS bf16x8*)(lds + PG8_SB(b, h) + boff + n * 2048 + k * 1024); } while (0)
; #define PG8_MMA(ai, bj, At, Bt) do { __builtin_amdgcn_s_setprio(1); _Pragma("unroll") for (int m = 0; m < 4; ++m) _Pragma("unroll") for (int n = 0; n < 2; ++n) _Pragma("unroll") for (int k = 0; k < 2; ++k) \
;         acc[ai][bj][m][n] = __builtin_amdgcn_mfma_f32_16x16x32_bf16(Bt[n][k], At[m][k], acc[ai][bj][m][n], 0, 0, 0); __builtin_amdgcn_s_setprio(0); } while (0)
; #define PG8_WAIT_V(n) asm volatile("s_waitcnt vmcnt(" #n ")" ::: "memory")
; #define PG8_WAIT_L(n) asm volatile("s_waitcnt lgkmcnt(" #n ")" ::: "memory")
; #define PG8_BAR __builtin_amdgcn_s_barrier()
; #define PG8_SCHED __builtin_amdgcn_sched_barrier(0)
; template <class Epi, class Sched, bool ALIGN_EPI = false, bool SP2 = false>
; __device__ __forceinline__ void gemm_phase(PG8_LAS unsigned char* lds, const Gemm g, const Sched& S, const Epi& E) {
;     ...
;             PG8_LDB(B0, 1, 0); PG8_LDB(B1, 1, 1); PG8_SCHED; PG8_LDA(At, 1, 0); PG8_STAGE(PG8_SA(0, 1), a2 + hstep, voffA);
;             PG8_WAIT_V(8); PG8_WAIT_L(0); PG8_BAR; PG8_MMA(0, 0, At, B0); PG8_MMA(0, 1, At, B1); PG8_BAR; PG8_SCHED;
;             PG8_LDA(At, 1, 1); PG8_STAGE(PG8_SB(1, 0), b3, voffB); PG8_STAGE(PG8_SB(1, 1), b3 + hstep, voffB); PG8_STAGE(PG8_SA(1, 0), a3, voffA);
;             PG8_WAIT_V(8); PG8_WAIT_L(0); PG8_BAR; PG8_MMA(1, 0, At, B0); PG8_MMA(1, 1, At, B1); PG8_BAR; PG8_SCHED;
.Lmy_peel_969_mid:
	s_add_i32 s58, 0, 0x18000
	s_add_i32 s59, 0, 0x1c000
	v_add_u32_e32 v140, s58, v190
	v_add_u32_e32 v176, s59, v190
	ds_read_b128 v[128:131], v140
	ds_read_b128 v[132:135], v140 offset:1024
	ds_read_b128 v[136:139], v140 offset:2048
	ds_read_b128 v[140:143], v140 offset:3072
	ds_read_b128 v[144:147], v176
	ds_read_b128 v[148:151], v176 offset:1024
	ds_read_b128 v[172:175], v176 offset:2048
	ds_read_b128 v[176:179], v176 offset:3072
	s_add_u32 s28, s28, 0x40000
	s_addc_u32 s29, s29, 0
	s_mov_b32 m0, s41
	ds_read_b128 v[180:183], v193 offset:32768
	ds_read_b128 v[184:187], v193 offset:33792
	ds_read_b128 v[196:199], v193 offset:34816
	ds_read_b128 v[200:203], v193 offset:35840
	ds_read_b128 v[204:207], v193 offset:36864
	ds_read_b128 v[208:211], v193 offset:37888
	ds_read_b128 v[212:215], v193 offset:38912
	ds_read_b128 v[216:219], v193 offset:39936
	global_load_lds_dwordx4 v158, s[28:29]
	s_mov_b32 m0, s42
	s_nop 0
	global_load_lds_dwordx4 v154, s[28:29]
	s_waitcnt vmcnt(8)
	s_waitcnt lgkmcnt(0)
	s_barrier
	s_setprio 1
	v_mfma_f32_16x16x32_bf16 v[124:127], v[128:131], v[180:183], v[124:127]
	v_mfma_f32_16x16x32_bf16 v[120:123], v[136:139], v[180:183], v[120:123]
	v_mfma_f32_16x16x32_bf16 v[108:111], v[128:131], v[196:199], v[108:111]
	v_mfma_f32_16x16x32_bf16 v[104:107], v[136:139], v[196:199], v[104:107]
	v_mfma_f32_16x16x32_bf16 v[92:95], v[128:131], v[204:207], v[92:95]
	v_mfma_f32_16x16x32_bf16 v[84:87], v[136:139], v[204:207], v[84:87]
	v_mfma_f32_16x16x32_bf16 v[76:79], v[128:131], v[212:215], v[76:79]
	v_mfma_f32_16x16x32_bf16 v[72:75], v[136:139], v[212:215], v[72:75]
	v_mfma_f32_16x16x32_bf16 v[124:127], v[132:135], v[184:187], v[124:127]
	v_mfma_f32_16x16x32_bf16 v[120:123], v[140:143], v[184:187], v[120:123]
	v_mfma_f32_16x16x32_bf16 v[108:111], v[132:135], v[200:203], v[108:111]
	v_mfma_f32_16x16x32_bf16 v[104:107], v[140:143], v[200:203], v[104:107]
	v_mfma_f32_16x16x32_bf16 v[92:95], v[132:135], v[208:211], v[92:95]
	v_mfma_f32_16x16x32_bf16 v[84:87], v[140:143], v[208:211], v[84:87]
	v_mfma_f32_16x16x32_bf16 v[76:79], v[132:135], v[216:219], v[76:79]
	v_mfma_f32_16x16x32_bf16 v[72:75], v[140:143], v[216:219], v[72:75]
	v_mfma_f32_16x16x32_bf16 v[116:119], v[144:147], v[180:183], v[116:119]
	v_mfma_f32_16x16x32_bf16 v[112:115], v[172:175], v[180:183], v[112:115]
	v_mfma_f32_16x16x32_bf16 v[100:103], v[144:147], v[196:199], v[100:103]
	v_mfma_f32_16x16x32_bf16 v[96:99], v[172:175], v[196:199], v[96:99]
	v_mfma_f32_16x16x32_bf16 v[88:91], v[144:147], v[204:207], v[88:91]
	v_mfma_f32_16x16x32_bf16 v[80:83], v[172:175], v[204:207], v[80:83]
	v_mfma_f32_16x16x32_bf16 v[68:71], v[144:147], v[212:215], v[68:71]
	v_mfma_f32_16x16x32_bf16 v[64:67], v[172:175], v[212:215], v[64:67]
	v_mfma_f32_16x16x32_bf16 v[116:119], v[148:151], v[184:187], v[116:119]
	v_mfma_f32_16x16x32_bf16 v[112:115], v[176:179], v[184:187], v[112:115]
	v_mfma_f32_16x16x32_bf16 v[100:103], v[148:151], v[200:203], v[100:103]
	v_mfma_f32_16x16x32_bf16 v[96:99], v[176:179], v[200:203], v[96:99]
	v_mfma_f32_16x16x32_bf16 v[88:91], v[148:151], v[208:211], v[88:91]
	v_mfma_f32_16x16x32_bf16 v[80:83], v[176:179], v[208:211], v[80:83]
	v_mfma_f32_16x16x32_bf16 v[68:71], v[148:151], v[216:219], v[68:71]
	v_mfma_f32_16x16x32_bf16 v[64:67], v[176:179], v[216:219], v[64:67]
	s_setprio 0
	s_barrier
	s_add_i32 s28, s58, s36
	s_mov_b32 m0, s28
	ds_read_b128 v[180:183], v193 offset:49152
	ds_read_b128 v[184:187], v193 offset:50176
	ds_read_b128 v[196:199], v193 offset:51200
	ds_read_b128 v[200:203], v193 offset:52224
	ds_read_b128 v[204:207], v193 offset:53248
	ds_read_b128 v[208:211], v193 offset:54272
	ds_read_b128 v[212:215], v193 offset:55296
	ds_read_b128 v[216:219], v193 offset:56320
	global_load_lds_dwordx4 v156, s[92:93]
	s_add_i32 m0, s28, 0x2000
	s_add_u32 s26, s26, 0x40080
	s_addc_u32 s27, s27, 0
	s_add_i32 s28, s59, s36
	global_load_lds_dwordx4 v152, s[92:93]
	s_mov_b32 m0, s28
	s_nop 0
	global_load_lds_dwordx4 v156, s[26:27]
	s_add_i32 m0, s28, 0x2000
	s_nop 0
	global_load_lds_dwordx4 v152, s[26:27]
	s_mov_b32 m0, s43
	s_nop 0
	global_load_lds_dwordx4 v158, s[94:95]
	s_mov_b32 m0, s44
	s_nop 0
	global_load_lds_dwordx4 v154, s[94:95]
	s_waitcnt vmcnt(8)
	s_waitcnt lgkmcnt(0)
	s_barrier
	s_setprio 1
	v_mfma_f32_16x16x32_bf16 v[60:63], v[128:131], v[180:183], v[60:63]
	v_mfma_f32_16x16x32_bf16 v[52:55], v[136:139], v[180:183], v[52:55]
	v_mfma_f32_16x16x32_bf16 v[44:47], v[128:131], v[196:199], v[44:47]
	v_mfma_f32_16x16x32_bf16 v[40:43], v[136:139], v[196:199], v[40:43]
	v_mfma_f32_16x16x32_bf16 v[28:31], v[128:131], v[204:207], v[28:31]
	v_mfma_f32_16x16x32_bf16 v[20:23], v[136:139], v[204:207], v[20:23]
	v_mfma_f32_16x16x32_bf16 v[12:15], v[128:131], v[212:215], v[12:15]
	v_mfma_f32_16x16x32_bf16 v[8:11], v[136:139], v[212:215], v[8:11]
	v_mfma_f32_16x16x32_bf16 v[60:63], v[132:135], v[184:187], v[60:63]
	v_mfma_f32_16x16x32_bf16 v[52:55], v[140:143], v[184:187], v[52:55]
	v_mfma_f32_16x16x32_bf16 v[44:47], v[132:135], v[200:203], v[44:47]
	v_mfma_f32_16x16x32_bf16 v[40:43], v[140:143], v[200:203], v[40:43]
	v_mfma_f32_16x16x32_bf16 v[28:31], v[132:135], v[208:211], v[28:31]
	v_mfma_f32_16x16x32_bf16 v[20:23], v[140:143], v[208:211], v[20:23]
	v_mfma_f32_16x16x32_bf16 v[12:15], v[132:135], v[216:219], v[12:15]
	v_mfma_f32_16x16x32_bf16 v[8:11], v[140:143], v[216:219], v[8:11]
	v_mfma_f32_16x16x32_bf16 v[56:59], v[144:147], v[180:183], v[56:59]
	v_mfma_f32_16x16x32_bf16 v[48:51], v[172:175], v[180:183], v[48:51]
	v_mfma_f32_16x16x32_bf16 v[36:39], v[144:147], v[196:199], v[36:39]
	v_mfma_f32_16x16x32_bf16 v[32:35], v[172:175], v[196:199], v[32:35]
	v_mfma_f32_16x16x32_bf16 v[24:27], v[144:147], v[204:207], v[24:27]
	v_mfma_f32_16x16x32_bf16 v[16:19], v[172:175], v[204:207], v[16:19]
	v_mfma_f32_16x16x32_bf16 v[4:7], v[144:147], v[212:215], v[4:7]
	v_mfma_f32_16x16x32_bf16 v[0:3], v[172:175], v[212:215], v[0:3]
	v_mfma_f32_16x16x32_bf16 v[56:59], v[148:151], v[184:187], v[56:59]
	v_mfma_f32_16x16x32_bf16 v[48:51], v[176:179], v[184:187], v[48:51]
	v_mfma_f32_16x16x32_bf16 v[36:39], v[148:151], v[200:203], v[36:39]
	v_mfma_f32_16x16x32_bf16 v[32:35], v[176:179], v[200:203], v[32:35]
	v_mfma_f32_16x16x32_bf16 v[24:27], v[148:151], v[208:211], v[24:27]
	v_mfma_f32_16x16x32_bf16 v[16:19], v[176:179], v[208:211], v[16:19]
	v_mfma_f32_16x16x32_bf16 v[4:7], v[148:151], v[216:219], v[4:7]
	v_mfma_f32_16x16x32_bf16 v[0:3], v[176:179], v[216:219], v[0:3]
	s_setprio 0
	s_barrier
	s_add_i32 s57, s57, 2
	s_add_u32 s24, s24, 0x100
	s_addc_u32 s25, s25, 0
	s_add_u32 s55, s55, 0x100
	s_addc_u32 s56, s56, 0
	s_cmp_gt_u32 s57, 13
	s_cbranch_scc0 .LBB0_969
	s_and_b64 vcc, exec, s[12:13]
	s_cbranch_vccz .LBB0_972
	s_barrier

; #define PG8_STAGE(bufoff, gbase, voff) do { _Pragma("unroll") for (int _i = 0; _i < 2; ++_i) \
;         __builtin_amdgcn_global_load_lds((const unsigned*)((const char*)(gbase) + (voff)[_i]), (PG8_LAS unsigned*)(lds + (bufoff) + ldsw + _i * 8192), 16, 0, 0); } while (0)
; #define PG8_LDA(dst, b, h) do { _Pragma("unroll") for (int m = 0; m < 4; ++m) _Pragma("unroll") for (int k = 0; k < 2; ++k) dst[m][k] = *(const PG8_LAS bf16x8*)(lds + PG8_SA(b, h) + aoff + m * 2048 + k * 1024); } while (0)
; #define PG8_LDB(dst, b, h) do { _Pragma("unroll") for (int n = 0; n < 2; ++n) _Pragma("unroll") for (int k = 0; k < 2; ++k) dst[n][k] = *(const PG8_LAS bf16x8*)(lds + PG8_SB(b, h) + boff + n * 2048 + k * 1024); } while (0)
; #define PG8_MMA(ai, bj, At, Bt) do { __builtin_amdgcn_s_setprio(1); _Pragma("unroll") for (int m = 0; m < 4; ++m) _Pragma("unroll") for (int n = 0; n < 2; ++n) _Pragma("unroll") for (int k = 0; k < 2; ++k) \
;         acc[ai][bj][m][n] = __builtin_amdgcn_mfma_f32_16x16x32_bf16(Bt[n][k], At[m][k], acc[ai][bj][m][n], 0, 0, 0); __builtin_amdgcn_s_setprio(0); } while (0)
; #define PG8_WAIT_V(n) asm volatile("s_waitcnt vmcnt(" #n ")" ::: "memory")
; #define PG8_WAIT_L(n) asm volatile("s_waitcnt lgkmcnt(" #n ")" ::: "memory")
; template <class Epi, class Sched, bool ALIGN_EPI = false, bool SP2 = false>
; __device__ __forceinline__ void gemm_phase(PG8_LAS unsigned char* lds, const Gemm g, const Sched& S, const Epi& E) {
;     ...
;             const bool last = (t == nt - 2);
;             const char* a1 = cA + (size_t)(t + 1) * kstep;
;             const char* a2 = last ? nA : cA + (size_t)(t + 2) * kstep; const char* b2 = last ? nB : cB + (size_t)(t + 2) * kstep;
;             const char* a3 = a2 + kstep; const char* b3 = b2 + kstep;
;             if (last && has_next) S.a_ready(nxt);
;             if constexpr (SP2) {
;             PG8_LDB(B0, 0, 0); PG8_LDB(B1, 0, 1); PG8_SCHED; PG8_LDA(At, 0, 0); PG8_STAGE(PG8_SA(1, 1), a1 + hstep, voffA);
;             PG8_WAIT_V(8); PG8_WAIT_L(0); PG8_BAR; PG8_MMA(0, 0, At, B0); PG8_MMA(0, 1, At, B1); PG8_BAR; PG8_SCHED;
;             PG8_LDA(At, 0, 1); PG8_STAGE(PG8_SB(0, 0), b2, voffB); PG8_STAGE(PG8_SB(0, 1), b2 + hstep, voffB); PG8_STAGE(PG8_SA(0, 0), a2, voffA);
;             PG8_WAIT_V(8); PG8_WAIT_L(0); PG8_BAR; PG8_MMA(1, 0, At, B0); PG8_MMA(1, 1, At, B1); PG8_BAR; PG8_SCHED;
.LBB0_1051:
	s_add_u32 s54, s24, 0x100
	s_addc_u32 s55, s25, 0
	s_mov_b32 s56, -2
	ds_read_b128 v[146:149], v153
	ds_read_b128 v[156:159], v153 offset:1024
	ds_read_b128 v[160:163], v153 offset:2048
	ds_read_b128 v[164:167], v153 offset:3072
	ds_read_b128 v[168:171], v154
	ds_read_b128 v[172:175], v154 offset:1024
	ds_read_b128 v[176:179], v154 offset:2048
	ds_read_b128 v[180:183], v154 offset:3072
	s_add_u32 s24, s22, 0x100
	s_addc_u32 s25, s23, 0
	s_cmp_eq_u32 s56, 40
	s_cselect_b32 s29, s3, s25
	s_cselect_b32 s28, s2, s24
	s_cselect_b32 s27, s21, s55
	s_cselect_b32 s26, s20, s54
	s_add_i32 m0, s38, 0xc000
	ds_read_b128 v[184:187], v155
	ds_read_b128 v[188:191], v155 offset:1024
	ds_read_b128 v[192:195], v155 offset:2048
	ds_read_b128 v[196:199], v155 offset:3072
	ds_read_b128 v[200:203], v155 offset:4096
	ds_read_b128 v[204:207], v155 offset:5120
	ds_read_b128 v[208:211], v155 offset:6144
	ds_read_b128 v[212:215], v155 offset:7168
	global_load_lds_dwordx4 v138, s[22:23]
	s_add_i32 m0, s38, 0xe000
	s_nop 0
	global_load_lds_dwordx4 v140, s[22:23]
	s_waitcnt vmcnt(8)
	s_waitcnt lgkmcnt(0)
	s_barrier
	s_setprio 1
	v_mfma_f32_16x16x32_bf16 v[124:127], v[146:149], v[184:187], 0
	v_mfma_f32_16x16x32_bf16 v[120:123], v[160:163], v[184:187], 0
	v_mfma_f32_16x16x32_bf16 v[116:119], v[146:149], v[192:195], 0
	v_mfma_f32_16x16x32_bf16 v[112:115], v[160:163], v[192:195], 0
	v_mfma_f32_16x16x32_bf16 v[92:95], v[146:149], v[200:203], 0
	v_mfma_f32_16x16x32_bf16 v[88:91], v[160:163], v[200:203], 0
	v_mfma_f32_16x16x32_bf16 v[76:79], v[146:149], v[208:211], 0
	v_mfma_f32_16x16x32_bf16 v[72:75], v[160:163], v[208:211], 0
	v_mfma_f32_16x16x32_bf16 v[124:127], v[156:159], v[188:191], v[124:127]
	v_mfma_f32_16x16x32_bf16 v[120:123], v[164:167], v[188:191], v[120:123]
	v_mfma_f32_16x16x32_bf16 v[116:119], v[156:159], v[196:199], v[116:119]
	v_mfma_f32_16x16x32_bf16 v[112:115], v[164:167], v[196:199], v[112:115]
	v_mfma_f32_16x16x32_bf16 v[92:95], v[156:159], v[204:207], v[92:95]
	v_mfma_f32_16x16x32_bf16 v[88:91], v[164:167], v[204:207], v[88:91]
	v_mfma_f32_16x16x32_bf16 v[76:79], v[156:159], v[212:215], v[76:79]
	v_mfma_f32_16x16x32_bf16 v[72:75], v[164:167], v[212:215], v[72:75]
	v_mfma_f32_16x16x32_bf16 v[108:111], v[168:171], v[184:187], 0
	v_mfma_f32_16x16x32_bf16 v[104:107], v[176:179], v[184:187], 0
	v_mfma_f32_16x16x32_bf16 v[100:103], v[168:171], v[192:195], 0
	v_mfma_f32_16x16x32_bf16 v[96:99], v[176:179], v[192:195], 0
	v_mfma_f32_16x16x32_bf16 v[84:87], v[168:171], v[200:203], 0
	v_mfma_f32_16x16x32_bf16 v[80:83], v[176:179], v[200:203], 0
	v_mfma_f32_16x16x32_bf16 v[68:71], v[168:171], v[208:211], 0
	v_mfma_f32_16x16x32_bf16 v[64:67], v[176:179], v[208:211], 0
	v_mfma_f32_16x16x32_bf16 v[108:111], v[172:175], v[188:191], v[108:111]
	v_mfma_f32_16x16x32_bf16 v[104:107], v[180:183], v[188:191], v[104:107]
	v_mfma_f32_16x16x32_bf16 v[100:103], v[172:175], v[196:199], v[100:103]
	v_mfma_f32_16x16x32_bf16 v[96:99], v[180:183], v[196:199], v[96:99]
	v_mfma_f32_16x16x32_bf16 v[84:87], v[172:175], v[204:207], v[84:87]
	v_mfma_f32_16x16x32_bf16 v[80:83], v[180:183], v[204:207], v[80:83]
	v_mfma_f32_16x16x32_bf16 v[68:71], v[172:175], v[212:215], v[68:71]
	v_mfma_f32_16x16x32_bf16 v[64:67], v[180:183], v[212:215], v[64:67]
	s_setprio 0
	s_barrier
	s_add_u32 s92, s26, s8
	s_addc_u32 s93, s27, s9
	s_add_u32 s94, s28, s8
	s_addc_u32 s95, s29, s9
	s_add_i32 s22, s46, s37
	s_mov_b32 m0, s22
	ds_read_b128 v[184:187], v155 offset:16384
	ds_read_b128 v[188:191], v155 offset:17408
	ds_read_b128 v[192:195], v155 offset:18432
	ds_read_b128 v[196:199], v155 offset:19456
	ds_read_b128 v[200:203], v155 offset:20480
	ds_read_b128 v[204:207], v155 offset:21504
	ds_read_b128 v[208:211], v155 offset:22528
	ds_read_b128 v[212:215], v155 offset:23552
	global_load_lds_dwordx4 v130, s[26:27]
	s_add_i32 m0, s22, 0x2000
	s_add_u32 s22, s26, 0xb0000
	s_addc_u32 s23, s27, 0
	s_add_i32 s57, s47, s37
	global_load_lds_dwordx4 v134, s[26:27]
	s_mov_b32 m0, s57
	s_nop 0
	global_load_lds_dwordx4 v130, s[22:23]
	s_add_i32 m0, s57, 0x2000
	s_nop 0
	global_load_lds_dwordx4 v134, s[22:23]
	s_mov_b32 m0, s38
	s_nop 0
	global_load_lds_dwordx4 v128, s[28:29]
	s_mov_b32 m0, s39
	s_nop 0
	global_load_lds_dwordx4 v132, s[28:29]
	s_waitcnt vmcnt(8)
	s_waitcnt lgkmcnt(0)
	s_barrier
	s_setprio 1
	v_mfma_f32_16x16x32_bf16 v[60:63], v[146:149], v[184:187], 0
	v_mfma_f32_16x16x32_bf16 v[56:59], v[160:163], v[184:187], 0
	v_mfma_f32_16x16x32_bf16 v[44:47], v[146:149], v[192:195], 0
	v_mfma_f32_16x16x32_bf16 v[40:43], v[160:163], v[192:195], 0
	v_mfma_f32_16x16x32_bf16 v[28:31], v[146:149], v[200:203], 0
	v_mfma_f32_16x16x32_bf16 v[24:27], v[160:163], v[200:203], 0
	v_mfma_f32_16x16x32_bf16 v[12:15], v[146:149], v[208:211], 0
	v_mfma_f32_16x16x32_bf16 v[8:11], v[160:163], v[208:211], 0
	v_mfma_f32_16x16x32_bf16 v[60:63], v[156:159], v[188:191], v[60:63]
	v_mfma_f32_16x16x32_bf16 v[56:59], v[164:167], v[188:191], v[56:59]
	v_mfma_f32_16x16x32_bf16 v[44:47], v[156:159], v[196:199], v[44:47]
	v_mfma_f32_16x16x32_bf16 v[40:43], v[164:167], v[196:199], v[40:43]
	v_mfma_f32_16x16x32_bf16 v[28:31], v[156:159], v[204:207], v[28:31]
	v_mfma_f32_16x16x32_bf16 v[24:27], v[164:167], v[204:207], v[24:27]
	v_mfma_f32_16x16x32_bf16 v[12:15], v[156:159], v[212:215], v[12:15]
	v_mfma_f32_16x16x32_bf16 v[8:11], v[164:167], v[212:215], v[8:11]
	v_mfma_f32_16x16x32_bf16 v[52:55], v[168:171], v[184:187], 0
	v_mfma_f32_16x16x32_bf16 v[48:51], v[176:179], v[184:187], 0
	v_mfma_f32_16x16x32_bf16 v[36:39], v[168:171], v[192:195], 0
	v_mfma_f32_16x16x32_bf16 v[32:35], v[176:179], v[192:195], 0
	v_mfma_f32_16x16x32_bf16 v[20:23], v[168:171], v[200:203], 0
	v_mfma_f32_16x16x32_bf16 v[16:19], v[176:179], v[200:203], 0
	v_mfma_f32_16x16x32_bf16 v[4:7], v[168:171], v[208:211], 0
	v_mfma_f32_16x16x32_bf16 v[0:3], v[176:179], v[208:211], 0
	v_mfma_f32_16x16x32_bf16 v[52:55], v[172:175], v[188:191], v[52:55]
	v_mfma_f32_16x16x32_bf16 v[48:51], v[180:183], v[188:191], v[48:51]
	v_mfma_f32_16x16x32_bf16 v[36:39], v[172:175], v[196:199], v[36:39]
	v_mfma_f32_16x16x32_bf16 v[32:35], v[180:183], v[196:199], v[32:35]
	v_mfma_f32_16x16x32_bf16 v[20:23], v[172:175], v[204:207], v[20:23]
	v_mfma_f32_16x16x32_bf16 v[16:19], v[180:183], v[204:207], v[16:19]
	v_mfma_f32_16x16x32_bf16 v[4:7], v[172:175], v[212:215], v[4:7]
	v_mfma_f32_16x16x32_bf16 v[0:3], v[180:183], v[212:215], v[0:3]
	s_setprio 0
	s_barrier
	s_branch .Lmy_peel_1052_mid
; #define PG8_STAGE(bufoff, gbase, voff) do { _Pragma("unroll") for (int _i = 0; _i < 2; ++_i) \
;         __builtin_amdgcn_global_load_lds((const unsigned*)((const char*)(gbase) + (voff)[_i]), (PG8_LAS unsigned*)(lds + (bufoff) + ldsw + _i * 8192), 16, 0, 0); } while (0)
; #define PG8_LDA(dst, b, h) do { _Pragma("unroll") for (int m = 0; m < 4; ++m) _Pragma("unroll") for (int k = 0; k < 2; ++k) dst[m][k] = *(const PG8_LAS bf16x8*)(lds + PG8_SA(b, h) + aoff + m * 2048 + k * 1024); } while (0)
; #define PG8_LDB(dst, b, h) do { _Pragma("unroll") for (int n = 0; n < 2; ++n) _Pragma("unroll") for (int k = 0; k < 2; ++k) dst[n][k] = *(const PG8_LAS bf16x8*)(lds + PG8_SB(b, h) + boff + n * 2048 + k * 1024); } while (0)
; #define PG8_MMA(ai, bj, At, Bt) do { __builtin_amdgcn_s_setprio(1); _Pragma("unroll") for (int m = 0; m < 4; ++m) _Pragma("unroll") for (int n = 0; n < 2; ++n) _Pragma("unroll") for (int k = 0; k < 2; ++k) \
;         acc[ai][bj][m][n] = __builtin_amdgcn_mfma_f32_16x16x32_bf16(Bt[n][k], At[m][k], acc[ai][bj][m][n], 0, 0, 0); __builtin_amdgcn_s_setprio(0); } while (0)
; #define PG8_WAIT_V(n) asm volatile("s_waitcnt vmcnt(" #n ")" ::: "memory")
; #define PG8_BAR __builtin_amdgcn_s_barrier()
; template <class Epi, class Sched, bool ALIGN_EPI = false, bool SP2 = false>
; __device__ __forceinline__ void gemm_phase(PG8_LAS unsigned char* lds, const Gemm g, const Sched& S, const Epi& E) {
;     ...
;         for (int t = 0; t < nt; t += 2) {
;             const bool last = (t == nt - 2);
;             const char* a1 = cA + (size_t)(t + 1) * kstep;
;             const char* a2 = last ? nA : cA + (size_t)(t + 2) * kstep; const char* b2 = last ? nB : cB + (size_t)(t + 2) * kstep;
;             const char* a3 = a2 + kstep; const char* b3 = b2 + kstep;
;             if (last && has_next) S.a_ready(nxt);
;             if constexpr (SP2) {
;             PG8_LDB(B0, 0, 0); PG8_LDB(B1, 0, 1); PG8_SCHED; PG8_LDA(At, 0, 0); PG8_STAGE(PG8_SA(1, 1), a1 + hstep, voffA);
;             PG8_WAIT_V(8); PG8_WAIT_L(0); PG8_BAR; PG8_MMA(0, 0, At, B0); PG8_MMA(0, 1, At, B1); PG8_BAR; PG8_SCHED;
;             PG8_LDA(At, 0, 1); PG8_STAGE(PG8_SB(0, 0), b2, voffB); PG8_STAGE(PG8_SB(0, 1), b2 + hstep, voffB); PG8_STAGE(PG8_SA(0, 0), a2, voffA);
;             PG8_WAIT_V(8); PG8_WAIT_L(0); PG8_BAR; PG8_MMA(1, 0, At, B0); PG8_MMA(1, 1, At, B1); PG8_BAR; PG8_SCHED;
.LBB0_1052:
	ds_read_b128 v[146:149], v153
	ds_read_b128 v[156:159], v153 offset:1024
	ds_read_b128 v[160:163], v153 offset:2048
	ds_read_b128 v[164:167], v153 offset:3072
	ds_read_b128 v[168:171], v154
	ds_read_b128 v[172:175], v154 offset:1024
	ds_read_b128 v[176:179], v154 offset:2048
	ds_read_b128 v[180:183], v154 offset:3072
	s_add_u32 s24, s22, 0x100
	s_addc_u32 s25, s23, 0
	s_cmp_eq_u32 s56, 40
	s_cselect_b32 s29, s3, s25
	s_cselect_b32 s28, s2, s24
	s_cselect_b32 s27, s21, s55
	s_cselect_b32 s26, s20, s54
	s_add_i32 m0, s38, 0xc000
	ds_read_b128 v[184:187], v155
	ds_read_b128 v[188:191], v155 offset:1024
	ds_read_b128 v[192:195], v155 offset:2048
	ds_read_b128 v[196:199], v155 offset:3072
	ds_read_b128 v[200:203], v155 offset:4096
	ds_read_b128 v[204:207], v155 offset:5120
	ds_read_b128 v[208:211], v155 offset:6144
	ds_read_b128 v[212:215], v155 offset:7168
	global_load_lds_dwordx4 v138, s[22:23]
	s_add_i32 m0, s38, 0xe000
	s_nop 0
	global_load_lds_dwordx4 v140, s[22:23]
	s_waitcnt vmcnt(8)
	s_waitcnt lgkmcnt(0)
	s_barrier
	s_setprio 1
	v_mfma_f32_16x16x32_bf16 v[124:127], v[146:149], v[184:187], v[124:127]
	v_mfma_f32_16x16x32_bf16 v[120:123], v[160:163], v[184:187], v[120:123]
	v_mfma_f32_16x16x32_bf16 v[116:119], v[146:149], v[192:195], v[116:119]
	v_mfma_f32_16x16x32_bf16 v[112:115], v[160:163], v[192:195], v[112:115]
	v_mfma_f32_16x16x32_bf16 v[92:95], v[146:149], v[200:203], v[92:95]
	v_mfma_f32_16x16x32_bf16 v[88:91], v[160:163], v[200:203], v[88:91]
	v_mfma_f32_16x16x32_bf16 v[76:79], v[146:149], v[208:211], v[76:79]
	v_mfma_f32_16x16x32_bf16 v[72:75], v[160:163], v[208:211], v[72:75]
	v_mfma_f32_16x16x32_bf16 v[124:127], v[156:159], v[188:191], v[124:127]
	v_mfma_f32_16x16x32_bf16 v[120:123], v[164:167], v[188:191], v[120:123]
	v_mfma_f32_16x16x32_bf16 v[116:119], v[156:159], v[196:199], v[116:119]
	v_mfma_f32_16x16x32_bf16 v[112:115], v[164:167], v[196:199], v[112:115]
	v_mfma_f32_16x16x32_bf16 v[92:95], v[156:159], v[204:207], v[92:95]
	v_mfma_f32_16x16x32_bf16 v[88:91], v[164:167], v[204:207], v[88:91]
	v_mfma_f32_16x16x32_bf16 v[76:79], v[156:159], v[212:215], v[76:79]
	v_mfma_f32_16x16x32_bf16 v[72:75], v[164:167], v[212:215], v[72:75]
	v_mfma_f32_16x16x32_bf16 v[108:111], v[168:171], v[184:187], v[108:111]
	v_mfma_f32_16x16x32_bf16 v[104:107], v[176:179], v[184:187], v[104:107]
	v_mfma_f32_16x16x32_bf16 v[100:103], v[168:171], v[192:195], v[100:103]
	v_mfma_f32_16x16x32_bf16 v[96:99], v[176:179], v[192:195], v[96:99]
	v_mfma_f32_16x16x32_bf16 v[84:87], v[168:171], v[200:203], v[84:87]
	v_mfma_f32_16x16x32_bf16 v[80:83], v[176:179], v[200:203], v[80:83]
	v_mfma_f32_16x16x32_bf16 v[68:71], v[168:171], v[208:211], v[68:71]
	v_mfma_f32_16x16x32_bf16 v[64:67], v[176:179], v[208:211], v[64:67]
	v_mfma_f32_16x16x32_bf16 v[108:111], v[172:175], v[188:191], v[108:111]
	v_mfma_f32_16x16x32_bf16 v[104:107], v[180:183], v[188:191], v[104:107]
	v_mfma_f32_16x16x32_bf16 v[100:103], v[172:175], v[196:199], v[100:103]
	v_mfma_f32_16x16x32_bf16 v[96:99], v[180:183], v[196:199], v[96:99]
	v_mfma_f32_16x16x32_bf16 v[84:87], v[172:175], v[204:207], v[84:87]
	v_mfma_f32_16x16x32_bf16 v[80:83], v[180:183], v[204:207], v[80:83]
	v_mfma_f32_16x16x32_bf16 v[68:71], v[172:175], v[212:215], v[68:71]
	v_mfma_f32_16x16x32_bf16 v[64:67], v[180:183], v[212:215], v[64:67]
	s_setprio 0
	s_barrier
	s_add_u32 s92, s26, s8
	s_addc_u32 s93, s27, s9
	s_add_u32 s94, s28, s8
	s_addc_u32 s95, s29, s9
	s_add_i32 s22, s46, s37
	s_mov_b32 m0, s22
	ds_read_b128 v[184:187], v155 offset:16384
	ds_read_b128 v[188:191], v155 offset:17408
	ds_read_b128 v[192:195], v155 offset:18432
	ds_read_b128 v[196:199], v155 offset:19456
	ds_read_b128 v[200:203], v155 offset:20480
	ds_read_b128 v[204:207], v155 offset:21504
	ds_read_b128 v[208:211], v155 offset:22528
	ds_read_b128 v[212:215], v155 offset:23552
	global_load_lds_dwordx4 v130, s[26:27]
	s_add_i32 m0, s22, 0x2000
	s_add_u32 s22, s26, 0xb0000
	s_addc_u32 s23, s27, 0
	s_add_i32 s57, s47, s37
	global_load_lds_dwordx4 v134, s[26:27]
	s_mov_b32 m0, s57
	s_nop 0
	global_load_lds_dwordx4 v130, s[22:23]
	s_add_i32 m0, s57, 0x2000
	s_nop 0
	global_load_lds_dwordx4 v134, s[22:23]
	s_mov_b32 m0, s38
	s_nop 0
	global_load_lds_dwordx4 v128, s[28:29]
	s_mov_b32 m0, s39
	s_nop 0
	global_load_lds_dwordx4 v132, s[28:29]
	s_waitcnt vmcnt(8)
	s_waitcnt lgkmcnt(0)
	s_barrier
	s_setprio 1
	v_mfma_f32_16x16x32_bf16 v[60:63], v[146:149], v[184:187], v[60:63]
	v_mfma_f32_16x16x32_bf16 v[56:59], v[160:163], v[184:187], v[56:59]
	v_mfma_f32_16x16x32_bf16 v[44:47], v[146:149], v[192:195], v[44:47]
	v_mfma_f32_16x16x32_bf16 v[40:43], v[160:163], v[192:195], v[40:43]
	v_mfma_f32_16x16x32_bf16 v[28:31], v[146:149], v[200:203], v[28:31]
	v_mfma_f32_16x16x32_bf16 v[24:27], v[160:163], v[200:203], v[24:27]
	v_mfma_f32_16x16x32_bf16 v[12:15], v[146:149], v[208:211], v[12:15]
	v_mfma_f32_16x16x32_bf16 v[8:11], v[160:163], v[208:211], v[8:11]
	v_mfma_f32_16x16x32_bf16 v[60:63], v[156:159], v[188:191], v[60:63]
	v_mfma_f32_16x16x32_bf16 v[56:59], v[164:167], v[188:191], v[56:59]
	v_mfma_f32_16x16x32_bf16 v[44:47], v[156:159], v[196:199], v[44:47]
	v_mfma_f32_16x16x32_bf16 v[40:43], v[164:167], v[196:199], v[40:43]
	v_mfma_f32_16x16x32_bf16 v[28:31], v[156:159], v[204:207], v[28:31]
	v_mfma_f32_16x16x32_bf16 v[24:27], v[164:167], v[204:207], v[24:27]
	v_mfma_f32_16x16x32_bf16 v[12:15], v[156:159], v[212:215], v[12:15]
	v_mfma_f32_16x16x32_bf16 v[8:11], v[164:167], v[212:215], v[8:11]
	v_mfma_f32_16x16x32_bf16 v[52:55], v[168:171], v[184:187], v[52:55]
	v_mfma_f32_16x16x32_bf16 v[48:51], v[176:179], v[184:187], v[48:51]
	v_mfma_f32_16x16x32_bf16 v[36:39], v[168:171], v[192:195], v[36:39]
	v_mfma_f32_16x16x32_bf16 v[32:35], v[176:179], v[192:195], v[32:35]
	v_mfma_f32_16x16x32_bf16 v[20:23], v[168:171], v[200:203], v[20:23]
	v_mfma_f32_16x16x32_bf16 v[16:19], v[176:179], v[200:203], v[16:19]
	v_mfma_f32_16x16x32_bf16 v[4:7], v[168:171], v[208:211], v[4:7]
	v_mfma_f32_16x16x32_bf16 v[0:3], v[176:179], v[208:211], v[0:3]
	v_mfma_f32_16x16x32_bf16 v[52:55], v[172:175], v[188:191], v[52:55]
	v_mfma_f32_16x16x32_bf16 v[48:51], v[180:183], v[188:191], v[48:51]
	v_mfma_f32_16x16x32_bf16 v[36:39], v[172:175], v[196:199], v[36:39]
	v_mfma_f32_16x16x32_bf16 v[32:35], v[180:183], v[196:199], v[32:35]
	v_mfma_f32_16x16x32_bf16 v[20:23], v[172:175], v[204:207], v[20:23]
	v_mfma_f32_16x16x32_bf16 v[16:19], v[180:183], v[204:207], v[16:19]
	v_mfma_f32_16x16x32_bf16 v[4:7], v[172:175], v[212:215], v[4:7]
	v_mfma_f32_16x16x32_bf16 v[0:3], v[180:183], v[212:215], v[0:3]
	s_setprio 0
	s_barrier
; #define PG8_STAGE(bufoff, gbase, voff) do { _Pragma("unroll") for (int _i = 0; _i < 2; ++_i) \
;         __builtin_amdgcn_global_load_lds((const unsigned*)((const char*)(gbase) + (voff)[_i]), (PG8_LAS unsigned*)(lds + (bufoff) + ldsw + _i * 8192), 16, 0, 0); } while (0)
; #define PG8_LDA(dst, b, h) do { _Pragma("unroll") for (int m = 0; m < 4; ++m) _Pragma("unroll") for (int k = 0; k < 2; ++k) dst[m][k] = *(const PG8_LAS bf16x8*)(lds + PG8_SA(b, h) + aoff + m * 2048 + k * 1024); } while (0)
; #define PG8_LDB(dst, b, h) do { _Pragma("unroll") for (int n = 0; n < 2; ++n) _Pragma("unroll") for (int k = 0; k < 2; ++k) dst[n][k] = *(const PG8_LAS bf16x8*)(lds + PG8_SB(b, h) + boff + n * 2048 + k * 1024); } while (0)
; #define PG8_MMA(ai, bj, At, Bt) do { __builtin_amdgcn_s_setprio(1); _Pragma("unroll") for (int m = 0; m < 4; ++m) _Pragma("unroll") for (int n = 0; n < 2; ++n) _Pragma("unroll") for (int k = 0; k < 2; ++k) \
;         acc[ai][bj][m][n] = __builtin_amdgcn_mfma_f32_16x16x32_bf16(Bt[n][k], At[m][k], acc[ai][bj][m][n], 0, 0, 0); __builtin_amdgcn_s_setprio(0); } while (0)
; #define PG8_WAIT_V(n) asm volatile("s_waitcnt vmcnt(" #n ")" ::: "memory")
; #define PG8_WAIT_L(n) asm volatile("s_waitcnt lgkmcnt(" #n ")" ::: "memory")
; #define PG8_BAR __builtin_amdgcn_s_barrier()
; #define PG8_SCHED __builtin_amdgcn_sched_barrier(0)
; template <class Epi, class Sched, bool ALIGN_EPI = false, bool SP2 = false>
; __device__ __forceinline__ void gemm_phase(PG8_LAS unsigned char* lds, const Gemm g, const Sched& S, const Epi& E) {
;     ...
;         for (int t = 0; t < nt; t += 2) {
;             const bool last = (t == nt - 2);
;             const char* a1 = cA + (size_t)(t + 1) * kstep;
;             const char* a2 = last ? nA : cA + (size_t)(t + 2) * kstep; const char* b2 = last ? nB : cB + (size_t)(t + 2) * kstep;
;     ...
;             PG8_LDB(B0, 1, 0); PG8_LDB(B1, 1, 1); PG8_SCHED; PG8_LDA(At, 1, 0); PG8_STAGE(PG8_SA(0, 1), a2 + hstep, voffA);
;             PG8_WAIT_V(8); PG8_WAIT_L(0); PG8_BAR; PG8_MMA(0, 0, At, B0); PG8_MMA(0, 1, At, B1); PG8_BAR; PG8_SCHED;
;             PG8_LDA(At, 1, 1); PG8_STAGE(PG8_SB(1, 0), b3, voffB); PG8_STAGE(PG8_SB(1, 1), b3 + hstep, voffB); PG8_STAGE(PG8_SA(1, 0), a3, voffA);
;             PG8_WAIT_V(8); PG8_WAIT_L(0); PG8_BAR; PG8_MMA(1, 0, At, B0); PG8_MMA(1, 1, At, B1); PG8_BAR; PG8_SCHED;
.Lmy_peel_1052_mid:
	s_add_i32 s57, 0, 0x18000
	s_add_i32 s58, 0, 0x1c000
	v_add_u32_e32 v164, s57, v152
	v_add_u32_e32 v180, s58, v152
	ds_read_b128 v[146:149], v164
	ds_read_b128 v[156:159], v164 offset:1024
	ds_read_b128 v[160:163], v164 offset:2048
	ds_read_b128 v[164:167], v164 offset:3072
	ds_read_b128 v[168:171], v180
	ds_read_b128 v[172:175], v180 offset:1024
	ds_read_b128 v[176:179], v180 offset:2048
	ds_read_b128 v[180:183], v180 offset:3072
	s_add_u32 s22, s28, 0xb0000
	s_addc_u32 s23, s29, 0
	s_mov_b32 m0, s40
	ds_read_b128 v[184:187], v155 offset:32768
	ds_read_b128 v[188:191], v155 offset:33792
	ds_read_b128 v[192:195], v155 offset:34816
	ds_read_b128 v[196:199], v155 offset:35840
	ds_read_b128 v[200:203], v155 offset:36864
	ds_read_b128 v[204:207], v155 offset:37888
	ds_read_b128 v[208:211], v155 offset:38912
	ds_read_b128 v[212:215], v155 offset:39936
	global_load_lds_dwordx4 v128, s[22:23]
	s_mov_b32 m0, s41
	s_nop 0
	global_load_lds_dwordx4 v132, s[22:23]
	s_waitcnt vmcnt(8)
	s_waitcnt lgkmcnt(0)
	s_barrier
	s_setprio 1
	v_mfma_f32_16x16x32_bf16 v[124:127], v[146:149], v[184:187], v[124:127]
	v_mfma_f32_16x16x32_bf16 v[120:123], v[160:163], v[184:187], v[120:123]
	v_mfma_f32_16x16x32_bf16 v[116:119], v[146:149], v[192:195], v[116:119]
	v_mfma_f32_16x16x32_bf16 v[112:115], v[160:163], v[192:195], v[112:115]
	v_mfma_f32_16x16x32_bf16 v[92:95], v[146:149], v[200:203], v[92:95]
	v_mfma_f32_16x16x32_bf16 v[88:91], v[160:163], v[200:203], v[88:91]
	v_mfma_f32_16x16x32_bf16 v[76:79], v[146:149], v[208:211], v[76:79]
	v_mfma_f32_16x16x32_bf16 v[72:75], v[160:163], v[208:211], v[72:75]
	v_mfma_f32_16x16x32_bf16 v[124:127], v[156:159], v[188:191], v[124:127]
	v_mfma_f32_16x16x32_bf16 v[120:123], v[164:167], v[188:191], v[120:123]
	v_mfma_f32_16x16x32_bf16 v[116:119], v[156:159], v[196:199], v[116:119]
	v_mfma_f32_16x16x32_bf16 v[112:115], v[164:167], v[196:199], v[112:115]
	v_mfma_f32_16x16x32_bf16 v[92:95], v[156:159], v[204:207], v[92:95]
	v_mfma_f32_16x16x32_bf16 v[88:91], v[164:167], v[204:207], v[88:91]
	v_mfma_f32_16x16x32_bf16 v[76:79], v[156:159], v[212:215], v[76:79]
	v_mfma_f32_16x16x32_bf16 v[72:75], v[164:167], v[212:215], v[72:75]
	v_mfma_f32_16x16x32_bf16 v[108:111], v[168:171], v[184:187], v[108:111]
	v_mfma_f32_16x16x32_bf16 v[104:107], v[176:179], v[184:187], v[104:107]
	v_mfma_f32_16x16x32_bf16 v[100:103], v[168:171], v[192:195], v[100:103]
	v_mfma_f32_16x16x32_bf16 v[96:99], v[176:179], v[192:195], v[96:99]
	v_mfma_f32_16x16x32_bf16 v[84:87], v[168:171], v[200:203], v[84:87]
	v_mfma_f32_16x16x32_bf16 v[80:83], v[176:179], v[200:203], v[80:83]
	v_mfma_f32_16x16x32_bf16 v[68:71], v[168:171], v[208:211], v[68:71]
	v_mfma_f32_16x16x32_bf16 v[64:67], v[176:179], v[208:211], v[64:67]
	v_mfma_f32_16x16x32_bf16 v[108:111], v[172:175], v[188:191], v[108:111]
	v_mfma_f32_16x16x32_bf16 v[104:107], v[180:183], v[188:191], v[104:107]
	v_mfma_f32_16x16x32_bf16 v[100:103], v[172:175], v[196:199], v[100:103]
	v_mfma_f32_16x16x32_bf16 v[96:99], v[180:183], v[196:199], v[96:99]
	v_mfma_f32_16x16x32_bf16 v[84:87], v[172:175], v[204:207], v[84:87]
	v_mfma_f32_16x16x32_bf16 v[80:83], v[180:183], v[204:207], v[80:83]
	v_mfma_f32_16x16x32_bf16 v[68:71], v[172:175], v[212:215], v[68:71]
	v_mfma_f32_16x16x32_bf16 v[64:67], v[180:183], v[212:215], v[64:67]
	s_setprio 0
	s_barrier
	s_add_i32 s22, s57, s37
	s_mov_b32 m0, s22
	ds_read_b128 v[184:187], v155 offset:49152
	ds_read_b128 v[188:191], v155 offset:50176
	ds_read_b128 v[192:195], v155 offset:51200
	ds_read_b128 v[196:199], v155 offset:52224
	ds_read_b128 v[200:203], v155 offset:53248
	ds_read_b128 v[204:207], v155 offset:54272
	ds_read_b128 v[208:211], v155 offset:55296
	ds_read_b128 v[212:215], v155 offset:56320
	global_load_lds_dwordx4 v130, s[92:93]
	s_add_i32 m0, s22, 0x2000
	s_add_u32 s22, s26, 0xb0080
	s_addc_u32 s23, s27, 0
	s_add_i32 s26, s58, s37
	global_load_lds_dwordx4 v134, s[92:93]
	s_mov_b32 m0, s26
	s_nop 0
	global_load_lds_dwordx4 v130, s[22:23]
	s_add_i32 m0, s26, 0x2000
	s_nop 0
	global_load_lds_dwordx4 v134, s[22:23]
	s_mov_b32 m0, s43
	s_nop 0
	global_load_lds_dwordx4 v128, s[94:95]
	s_mov_b32 m0, s44
	s_nop 0
	global_load_lds_dwordx4 v132, s[94:95]
	s_waitcnt vmcnt(8)
	s_waitcnt lgkmcnt(0)
	s_barrier
	s_setprio 1
	v_mfma_f32_16x16x32_bf16 v[60:63], v[146:149], v[184:187], v[60:63]
	v_mfma_f32_16x16x32_bf16 v[56:59], v[160:163], v[184:187], v[56:59]
	v_mfma_f32_16x16x32_bf16 v[44:47], v[146:149], v[192:195], v[44:47]
	v_mfma_f32_16x16x32_bf16 v[40:43], v[160:163], v[192:195], v[40:43]
	v_mfma_f32_16x16x32_bf16 v[28:31], v[146:149], v[200:203], v[28:31]
	v_mfma_f32_16x16x32_bf16 v[24:27], v[160:163], v[200:203], v[24:27]
	v_mfma_f32_16x16x32_bf16 v[12:15], v[146:149], v[208:211], v[12:15]
	v_mfma_f32_16x16x32_bf16 v[8:11], v[160:163], v[208:211], v[8:11]
	v_mfma_f32_16x16x32_bf16 v[60:63], v[156:159], v[188:191], v[60:63]
	v_mfma_f32_16x16x32_bf16 v[56:59], v[164:167], v[188:191], v[56:59]
	v_mfma_f32_16x16x32_bf16 v[44:47], v[156:159], v[196:199], v[44:47]
	v_mfma_f32_16x16x32_bf16 v[40:43], v[164:167], v[196:199], v[40:43]
	v_mfma_f32_16x16x32_bf16 v[28:31], v[156:159], v[204:207], v[28:31]
	v_mfma_f32_16x16x32_bf16 v[24:27], v[164:167], v[204:207], v[24:27]
	v_mfma_f32_16x16x32_bf16 v[12:15], v[156:159], v[212:215], v[12:15]
	v_mfma_f32_16x16x32_bf16 v[8:11], v[164:167], v[212:215], v[8:11]
	v_mfma_f32_16x16x32_bf16 v[52:55], v[168:171], v[184:187], v[52:55]
	v_mfma_f32_16x16x32_bf16 v[48:51], v[176:179], v[184:187], v[48:51]
	v_mfma_f32_16x16x32_bf16 v[36:39], v[168:171], v[192:195], v[36:39]
	v_mfma_f32_16x16x32_bf16 v[32:35], v[176:179], v[192:195], v[32:35]
	v_mfma_f32_16x16x32_bf16 v[20:23], v[168:171], v[200:203], v[20:23]
	v_mfma_f32_16x16x32_bf16 v[16:19], v[176:179], v[200:203], v[16:19]
	v_mfma_f32_16x16x32_bf16 v[4:7], v[168:171], v[208:211], v[4:7]
	v_mfma_f32_16x16x32_bf16 v[0:3], v[176:179], v[208:211], v[0:3]
	v_mfma_f32_16x16x32_bf16 v[52:55], v[172:175], v[188:191], v[52:55]
	v_mfma_f32_16x16x32_bf16 v[48:51], v[180:183], v[188:191], v[48:51]
	v_mfma_f32_16x16x32_bf16 v[36:39], v[172:175], v[196:199], v[36:39]
	v_mfma_f32_16x16x32_bf16 v[32:35], v[180:183], v[196:199], v[32:35]
	v_mfma_f32_16x16x32_bf16 v[20:23], v[172:175], v[204:207], v[20:23]
	v_mfma_f32_16x16x32_bf16 v[16:19], v[180:183], v[204:207], v[16:19]
	v_mfma_f32_16x16x32_bf16 v[4:7], v[172:175], v[212:215], v[4:7]
	v_mfma_f32_16x16x32_bf16 v[0:3], v[180:183], v[212:215], v[0:3]
	s_setprio 0
	s_barrier
	s_add_i32 s56, s56, 2
	s_add_u32 s54, s54, 0x100
	s_addc_u32 s55, s55, 0
	s_cmp_gt_u32 s56, 41
	s_mov_b64 s[22:23], s[24:25]
	s_cbranch_scc0 .LBB0_1052
	s_and_b64 vcc, exec, s[10:11]
	s_cbranch_vccz .LBB0_1055
	s_barrier
